# EpiResid xb (bf16 copy) stores widened: dwordx2 pairs merged into dwordx4 via 8 extra VGPRs (alloc 240->248)
# speedup vs baseline: 1.0053x; 1.0001x over previous
; __device__ __forceinline__ unsigned pk2(float lo, float hi) { f32x2_t v = {lo, hi}; bf16x2_t b = __builtin_convertvector(v, bf16x2_t); return __builtin_bit_cast(unsigned, b); }
; __device__ __forceinline__ float xor16_sum(float v) { float a = v, b = v; swap16(a, b); return a + b; }
; __device__ __forceinline__ float xor32_sum(float v) { float a = v, b = v; swap32(a, b); return a + b; }
;     __device__ __forceinline__ void operator()(const f32x4 (&acc)[2][2][4][2], const Unit& u, int wr, int wc, int fr, int fq) const {
;     ...
;                 const int row = row0 + ai * HALF + m * 16; float sq = 0.f;
; #pragma unroll
;                 for (int bj = 0; bj < 2; ++bj)
; #pragma unroll
;                     for (int n = 0; n < 2; ++n) {
;                         const size_t idx = (size_t)row * ldc + u.pn * BM + bj * HALF + wc * 32 + 8 * fq + 4 * n;
;                         const f32x4 b = *(const f32x4*)(base + idx);
;                         const f32x4 v = b + acc[ai][bj][m][n] * alpha;
;                         *(f32x4*)(out + idx) = v;
;                         if (NORM) { u32x2 w; w.x = pk2(v[0], v[1]); w.y = pk2(v[2], v[3]); *(u32x2*)(xb + idx) = w; sq += (v[0] * v[0] + v[1] * v[1]) + (v[2] * v[2] + v[3] * v[3]); }
;                     }
;                 if (NORM) { sq = xor16_sum(sq); sq = xor32_sum(sq); if (fq == 0) __hip_atomic_fetch_add(ss + row, sq, __ATOMIC_RELAXED, __HIP_MEMORY_SCOPE_AGENT); }
.LBB0_423:
	v_lshl_add_u32 v148, s14, 8, v137
	s_lshl_b32 s12, s16, 8
	s_ashr_i32 s13, s12, 31
	v_ashrrev_i32_e32 v149, 31, v148
	v_mov_b32_e32 v147, s13
	v_or_b32_e32 v146, s12, v136
	v_lshlrev_b64 v[154:155], 11, v[148:149]
	v_lshl_add_u64 v[158:159], v[154:155], 0, v[146:147]
	v_lshlrev_b64 v[160:161], 2, v[158:159]
	v_lshl_add_u64 v[162:163], s[52:53], 0, v[160:161]
	v_mov_b32_e32 v232, v162
	v_mov_b32_e32 v233, v163
	v_mov_b32_e32 v231, 0
	v_mov_b32_e32 v230, 0x0
	v_lshl_add_u64 v[228:229], v[232:233], 0, v[230:231]
	global_load_dwordx4 v[164:167], v[228:229], off nt
	global_load_dwordx4 v[168:171], v[228:229], off offset:16 nt
	global_load_dwordx4 v[172:175], v[228:229], off offset:512 nt
	global_load_dwordx4 v[176:179], v[228:229], off offset:528 nt
	v_mov_b32_e32 v230, 0x20000
	v_lshl_add_u64 v[228:229], v[232:233], 0, v[230:231]
	global_load_dwordx4 v[180:183], v[228:229], off nt
	global_load_dwordx4 v[188:191], v[228:229], off offset:16 nt
	global_load_dwordx4 v[192:195], v[228:229], off offset:512 nt
	global_load_dwordx4 v[196:199], v[228:229], off offset:528 nt
	v_mov_b32_e32 v230, 0x40000
	v_lshl_add_u64 v[228:229], v[232:233], 0, v[230:231]
	global_load_dwordx4 v[200:203], v[228:229], off nt
	global_load_dwordx4 v[204:207], v[228:229], off offset:16 nt
	global_load_dwordx4 v[208:211], v[228:229], off offset:512 nt
	global_load_dwordx4 v[212:215], v[228:229], off offset:528 nt
	v_mov_b32_e32 v230, 0x60000
	v_lshl_add_u64 v[228:229], v[232:233], 0, v[230:231]
	global_load_dwordx4 v[216:219], v[228:229], off nt
	global_load_dwordx4 v[220:223], v[228:229], off offset:16 nt
	global_load_dwordx4 v[224:227], v[228:229], off offset:512 nt
	global_load_dwordx4 v[234:237], v[228:229], off offset:528 nt
	s_nop 0
	v_lshlrev_b64 v[158:159], 1, v[158:159]
	s_nop 0
	s_waitcnt vmcnt(12)
	v_pk_fma_f32 v[126:127], v[126:127], 0.5, v[166:167] op_sel_hi:[1,0,1]
	v_pk_fma_f32 v[124:125], v[124:125], 0.5, v[164:165] op_sel_hi:[1,0,1]
	v_lshl_add_u64 v[154:155], s[30:31], 0, v[160:161]
	global_store_dwordx4 v[154:155], v[124:127], off
	v_cvt_pk_bf16_f32 v240, v124, v125
	v_cvt_pk_bf16_f32 v241, v126, v127
	v_mul_f32_e32 v125, v125, v125
	v_lshl_add_u64 v[160:161], s[40:41], 0, v[158:159]
	v_fmac_f32_e32 v125, v124, v124
	v_mul_f32_e32 v124, v127, v127
	s_nop 0
	v_fmac_f32_e32 v124, v126, v126
	v_add_f32_e32 v156, v125, v124
	s_nop 0
	s_nop 0
	v_pk_fma_f32 v[122:123], v[122:123], 0.5, v[170:171] op_sel_hi:[1,0,1]
	v_pk_fma_f32 v[120:121], v[120:121], 0.5, v[168:169] op_sel_hi:[1,0,1]
	global_store_dwordx4 v[154:155], v[120:123], off offset:16
	v_cvt_pk_bf16_f32 v242, v120, v121
	v_or_b32_e32 v126, 8, v158
	v_mul_f32_e32 v121, v121, v121
	v_mov_b32_e32 v127, v159
	v_fmac_f32_e32 v121, v120, v120
	v_mul_f32_e32 v120, v123, v123
	v_cvt_pk_bf16_f32 v243, v122, v123
	v_lshl_add_u64 v[126:127], s[40:41], 0, v[126:127]
	v_fmac_f32_e32 v120, v122, v122
	global_store_dwordx4 v[126:127], v[240:243], off offset:-8
	v_add_f32_e32 v120, v121, v120
	v_add_f32_e32 v124, v156, v120
	s_nop 0
	s_nop 0
	v_pk_fma_f32 v[118:119], v[118:119], 0.5, v[174:175] op_sel_hi:[1,0,1]
	v_pk_fma_f32 v[116:117], v[116:117], 0.5, v[172:173] op_sel_hi:[1,0,1]
	global_store_dwordx4 v[154:155], v[116:119], off offset:512
	v_cvt_pk_bf16_f32 v240, v116, v117
	v_or_b32_e32 v122, 0x100, v158
	v_mul_f32_e32 v117, v117, v117
	v_mov_b32_e32 v123, v159
	v_fmac_f32_e32 v117, v116, v116
	v_mul_f32_e32 v116, v119, v119
	v_cvt_pk_bf16_f32 v241, v118, v119
	v_lshl_add_u64 v[122:123], s[40:41], 0, v[122:123]
	v_fmac_f32_e32 v116, v118, v118
	s_nop 0
	v_add_f32_e32 v116, v117, v116
	v_add_f32_e32 v120, v124, v116
	s_nop 0
	v_or_b32_e32 v158, 0x108, v158
	s_nop 0
	v_pk_fma_f32 v[114:115], v[114:115], 0.5, v[178:179] op_sel_hi:[1,0,1]
	v_pk_fma_f32 v[112:113], v[112:113], 0.5, v[176:177] op_sel_hi:[1,0,1]
	v_mov_b32_e32 v230, 0x100000
	v_lshl_add_u64 v[228:229], v[232:233], 0, v[230:231]
	global_load_dwordx4 v[164:167], v[228:229], off nt
	global_load_dwordx4 v[168:171], v[228:229], off offset:16 nt
	global_load_dwordx4 v[172:175], v[228:229], off offset:512 nt
	global_load_dwordx4 v[176:179], v[228:229], off offset:528 nt
	global_store_dwordx4 v[154:155], v[112:115], off offset:528
	v_cvt_pk_bf16_f32 v242, v112, v113
	v_cvt_pk_bf16_f32 v243, v114, v115
	v_mul_f32_e32 v113, v113, v113
	v_fmac_f32_e32 v113, v112, v112
	v_mul_f32_e32 v112, v115, v115
	v_fmac_f32_e32 v112, v114, v114
	v_add_f32_e32 v112, v113, v112
	v_add_f32_e32 v112, v120, v112
	v_mov_b32_e32 v113, v112
	s_nop 1
	v_permlane16_swap_b32 v112, v113
	v_lshl_add_u64 v[118:119], s[40:41], 0, v[158:159]
	v_add_f32_e32 v112, v112, v113
	v_mov_b32_e32 v113, v112
	global_store_dwordx4 v[118:119], v[240:243], off offset:-8
	s_nop 1
	v_permlane32_swap_b32 v112, v113
	s_and_saveexec_b64 s[12:13], s[2:3]
	s_cbranch_execz .LBB0_425
	v_lshl_add_u64 v[114:115], v[148:149], 2, s[90:91]
	v_add_f32_e32 v112, v112, v113
	global_atomic_add_f32 v[114:115], v112, off
; __device__ __forceinline__ unsigned pk2(float lo, float hi) { f32x2_t v = {lo, hi}; bf16x2_t b = __builtin_convertvector(v, bf16x2_t); return __builtin_bit_cast(unsigned, b); }
; __device__ __forceinline__ float xor16_sum(float v) { float a = v, b = v; swap16(a, b); return a + b; }
; __device__ __forceinline__ float xor32_sum(float v) { float a = v, b = v; swap32(a, b); return a + b; }
;     __device__ __forceinline__ void operator()(const f32x4 (&acc)[2][2][4][2], const Unit& u, int wr, int wc, int fr, int fq) const {
;     ...
;                 const int row = row0 + ai * HALF + m * 16; float sq = 0.f;
; #pragma unroll
;                 for (int bj = 0; bj < 2; ++bj)
; #pragma unroll
;                     for (int n = 0; n < 2; ++n) {
;                         const size_t idx = (size_t)row * ldc + u.pn * BM + bj * HALF + wc * 32 + 8 * fq + 4 * n;
;                         const f32x4 b = *(const f32x4*)(base + idx);
;                         const f32x4 v = b + acc[ai][bj][m][n] * alpha;
;                         *(f32x4*)(out + idx) = v;
;                         if (NORM) { u32x2 w; w.x = pk2(v[0], v[1]); w.y = pk2(v[2], v[3]); *(u32x2*)(xb + idx) = w; sq += (v[0] * v[0] + v[1] * v[1]) + (v[2] * v[2] + v[3] * v[3]); }
;                     }
;                 if (NORM) { sq = xor16_sum(sq); sq = xor32_sum(sq); if (fq == 0) __hip_atomic_fetch_add(ss + row, sq, __ATOMIC_RELAXED, __HIP_MEMORY_SCOPE_AGENT); }
.LBB0_425:
	s_or_b64 exec, exec, s[12:13]
	v_or_b32_e32 v112, 16, v148
	v_ashrrev_i32_e32 v113, 31, v112
	v_lshlrev_b64 v[114:115], 11, v[112:113]
	v_lshl_add_u64 v[118:119], v[114:115], 0, v[146:147]
	v_lshlrev_b64 v[120:121], 2, v[118:119]
	v_lshl_add_u64 v[122:123], s[52:53], 0, v[120:121]
	s_nop 0
	v_lshlrev_b64 v[118:119], 1, v[118:119]
	s_nop 0
	s_waitcnt vmcnt(18)
	v_pk_fma_f32 v[110:111], v[110:111], 0.5, v[182:183] op_sel_hi:[1,0,1]
	v_pk_fma_f32 v[108:109], v[108:109], 0.5, v[180:181] op_sel_hi:[1,0,1]
	v_lshl_add_u64 v[114:115], s[30:31], 0, v[120:121]
	global_store_dwordx4 v[114:115], v[108:111], off
	v_cvt_pk_bf16_f32 v240, v108, v109
	v_cvt_pk_bf16_f32 v241, v110, v111
	v_mul_f32_e32 v109, v109, v109
	v_lshl_add_u64 v[120:121], s[40:41], 0, v[118:119]
	v_fmac_f32_e32 v109, v108, v108
	v_mul_f32_e32 v108, v111, v111
	s_nop 0
	v_fmac_f32_e32 v108, v110, v110
	v_add_f32_e32 v116, v109, v108
	s_nop 0
	s_nop 0
	v_pk_fma_f32 v[106:107], v[106:107], 0.5, v[190:191] op_sel_hi:[1,0,1]
	v_pk_fma_f32 v[104:105], v[104:105], 0.5, v[188:189] op_sel_hi:[1,0,1]
	global_store_dwordx4 v[114:115], v[104:107], off offset:16
	v_cvt_pk_bf16_f32 v242, v104, v105
	v_or_b32_e32 v110, 8, v118
	v_mul_f32_e32 v105, v105, v105
	v_mov_b32_e32 v111, v119
	v_fmac_f32_e32 v105, v104, v104
	v_mul_f32_e32 v104, v107, v107
	v_cvt_pk_bf16_f32 v243, v106, v107
	v_lshl_add_u64 v[110:111], s[40:41], 0, v[110:111]
	v_fmac_f32_e32 v104, v106, v106
	global_store_dwordx4 v[110:111], v[240:243], off offset:-8
	v_add_f32_e32 v104, v105, v104
	v_add_f32_e32 v108, v116, v104
	s_nop 0
	s_nop 0
	v_pk_fma_f32 v[102:103], v[102:103], 0.5, v[194:195] op_sel_hi:[1,0,1]
	v_pk_fma_f32 v[100:101], v[100:101], 0.5, v[192:193] op_sel_hi:[1,0,1]
	global_store_dwordx4 v[114:115], v[100:103], off offset:512
	v_cvt_pk_bf16_f32 v240, v100, v101
	v_or_b32_e32 v106, 0x100, v118
	v_mul_f32_e32 v101, v101, v101
	v_mov_b32_e32 v107, v119
	v_fmac_f32_e32 v101, v100, v100
	v_mul_f32_e32 v100, v103, v103
	v_cvt_pk_bf16_f32 v241, v102, v103
	v_lshl_add_u64 v[106:107], s[40:41], 0, v[106:107]
	v_fmac_f32_e32 v100, v102, v102
	s_nop 0
	v_add_f32_e32 v100, v101, v100
	v_add_f32_e32 v104, v108, v100
	s_nop 0
	v_or_b32_e32 v118, 0x108, v118
	s_nop 0
	v_pk_fma_f32 v[98:99], v[98:99], 0.5, v[198:199] op_sel_hi:[1,0,1]
	v_pk_fma_f32 v[96:97], v[96:97], 0.5, v[196:197] op_sel_hi:[1,0,1]
	v_mov_b32_e32 v230, 0x120000
	v_lshl_add_u64 v[228:229], v[232:233], 0, v[230:231]
	global_load_dwordx4 v[180:183], v[228:229], off nt
	global_load_dwordx4 v[188:191], v[228:229], off offset:16 nt
	global_load_dwordx4 v[192:195], v[228:229], off offset:512 nt
	global_load_dwordx4 v[196:199], v[228:229], off offset:528 nt
	global_store_dwordx4 v[114:115], v[96:99], off offset:528
	v_cvt_pk_bf16_f32 v242, v96, v97
	v_cvt_pk_bf16_f32 v243, v98, v99
	v_mul_f32_e32 v97, v97, v97
	v_fmac_f32_e32 v97, v96, v96
	v_mul_f32_e32 v96, v99, v99
	v_fmac_f32_e32 v96, v98, v98
	v_add_f32_e32 v96, v97, v96
	v_add_f32_e32 v96, v104, v96
	v_mov_b32_e32 v97, v96
	s_nop 1
	v_permlane16_swap_b32 v96, v97
	v_lshl_add_u64 v[102:103], s[40:41], 0, v[118:119]
	v_add_f32_e32 v96, v96, v97
	v_mov_b32_e32 v97, v96
	global_store_dwordx4 v[102:103], v[240:243], off offset:-8
	s_nop 1
	v_permlane32_swap_b32 v96, v97
	s_and_saveexec_b64 s[12:13], s[2:3]
	s_cbranch_execz .LBB0_427
	v_lshl_add_u64 v[98:99], v[112:113], 2, s[90:91]
	v_add_f32_e32 v96, v96, v97
	global_atomic_add_f32 v[98:99], v96, off
.LBB0_427:
	s_or_b64 exec, exec, s[12:13]
	v_or_b32_e32 v96, 32, v148
	v_ashrrev_i32_e32 v97, 31, v96
	v_lshlrev_b64 v[98:99], 11, v[96:97]
	v_lshl_add_u64 v[102:103], v[98:99], 0, v[146:147]
	v_lshlrev_b64 v[104:105], 2, v[102:103]
	v_lshl_add_u64 v[106:107], s[52:53], 0, v[104:105]
	s_nop 0
	v_lshlrev_b64 v[102:103], 1, v[102:103]
	s_nop 0
	s_waitcnt vmcnt(24)
	v_pk_fma_f32 v[94:95], v[94:95], 0.5, v[202:203] op_sel_hi:[1,0,1]
	v_pk_fma_f32 v[92:93], v[92:93], 0.5, v[200:201] op_sel_hi:[1,0,1]
	v_lshl_add_u64 v[98:99], s[30:31], 0, v[104:105]
	global_store_dwordx4 v[98:99], v[92:95], off
	v_cvt_pk_bf16_f32 v240, v92, v93
	v_cvt_pk_bf16_f32 v241, v94, v95
	v_mul_f32_e32 v93, v93, v93
	v_lshl_add_u64 v[104:105], s[40:41], 0, v[102:103]
	v_fmac_f32_e32 v93, v92, v92
	v_mul_f32_e32 v92, v95, v95
	s_nop 0
	v_fmac_f32_e32 v92, v94, v94
	v_add_f32_e32 v100, v93, v92
	s_nop 0
	s_nop 0
	v_pk_fma_f32 v[90:91], v[90:91], 0.5, v[206:207] op_sel_hi:[1,0,1]
	v_pk_fma_f32 v[88:89], v[88:89], 0.5, v[204:205] op_sel_hi:[1,0,1]
	global_store_dwordx4 v[98:99], v[88:91], off offset:16
	v_cvt_pk_bf16_f32 v242, v88, v89
	v_or_b32_e32 v94, 8, v102
	v_mul_f32_e32 v89, v89, v89
	v_mov_b32_e32 v95, v103
	v_fmac_f32_e32 v89, v88, v88
	v_mul_f32_e32 v88, v91, v91
	v_cvt_pk_bf16_f32 v243, v90, v91
	v_lshl_add_u64 v[94:95], s[40:41], 0, v[94:95]
	v_fmac_f32_e32 v88, v90, v90
	global_store_dwordx4 v[94:95], v[240:243], off offset:-8
	v_add_f32_e32 v88, v89, v88
	v_add_f32_e32 v92, v100, v88
	s_nop 0
	s_nop 0
	v_pk_fma_f32 v[86:87], v[86:87], 0.5, v[210:211] op_sel_hi:[1,0,1]
	v_pk_fma_f32 v[84:85], v[84:85], 0.5, v[208:209] op_sel_hi:[1,0,1]
	global_store_dwordx4 v[98:99], v[84:87], off offset:512
	v_cvt_pk_bf16_f32 v240, v84, v85
	v_or_b32_e32 v90, 0x100, v102
	v_mul_f32_e32 v85, v85, v85
	v_mov_b32_e32 v91, v103
	v_fmac_f32_e32 v85, v84, v84
	v_mul_f32_e32 v84, v87, v87
	v_cvt_pk_bf16_f32 v241, v86, v87
	v_lshl_add_u64 v[90:91], s[40:41], 0, v[90:91]
	v_fmac_f32_e32 v84, v86, v86
	s_nop 0
	v_add_f32_e32 v84, v85, v84
	v_add_f32_e32 v88, v92, v84
	s_nop 0
	v_or_b32_e32 v102, 0x108, v102
	s_nop 0
	v_pk_fma_f32 v[82:83], v[82:83], 0.5, v[214:215] op_sel_hi:[1,0,1]
	v_pk_fma_f32 v[80:81], v[80:81], 0.5, v[212:213] op_sel_hi:[1,0,1]
	v_mov_b32_e32 v230, 0x140000
	v_lshl_add_u64 v[228:229], v[232:233], 0, v[230:231]
	global_load_dwordx4 v[200:203], v[228:229], off nt
	global_load_dwordx4 v[204:207], v[228:229], off offset:16 nt
	global_load_dwordx4 v[208:211], v[228:229], off offset:512 nt
	global_load_dwordx4 v[212:215], v[228:229], off offset:528 nt
	global_store_dwordx4 v[98:99], v[80:83], off offset:528
	v_cvt_pk_bf16_f32 v242, v80, v81
	v_cvt_pk_bf16_f32 v243, v82, v83
	v_mul_f32_e32 v81, v81, v81
	v_fmac_f32_e32 v81, v80, v80
	v_mul_f32_e32 v80, v83, v83
	v_fmac_f32_e32 v80, v82, v82
	v_add_f32_e32 v80, v81, v80
	v_add_f32_e32 v80, v88, v80
	v_mov_b32_e32 v81, v80
	s_nop 1
	v_permlane16_swap_b32 v80, v81
	v_lshl_add_u64 v[86:87], s[40:41], 0, v[102:103]
	v_add_f32_e32 v80, v80, v81
	v_mov_b32_e32 v81, v80
	global_store_dwordx4 v[86:87], v[240:243], off offset:-8
	s_nop 1
	v_permlane32_swap_b32 v80, v81
	s_and_saveexec_b64 s[12:13], s[2:3]
	s_cbranch_execz .LBB0_429
	v_lshl_add_u64 v[82:83], v[96:97], 2, s[90:91]
	v_add_f32_e32 v80, v80, v81
	global_atomic_add_f32 v[82:83], v80, off
; __device__ __forceinline__ unsigned pk2(float lo, float hi) { f32x2_t v = {lo, hi}; bf16x2_t b = __builtin_convertvector(v, bf16x2_t); return __builtin_bit_cast(unsigned, b); }
; __device__ __forceinline__ float xor16_sum(float v) { float a = v, b = v; swap16(a, b); return a + b; }
; __device__ __forceinline__ float xor32_sum(float v) { float a = v, b = v; swap32(a, b); return a + b; }
;     __device__ __forceinline__ void operator()(const f32x4 (&acc)[2][2][4][2], const Unit& u, int wr, int wc, int fr, int fq) const {
;     ...
;                 const int row = row0 + ai * HALF + m * 16; float sq = 0.f;
; #pragma unroll
;                 for (int bj = 0; bj < 2; ++bj)
; #pragma unroll
;                     for (int n = 0; n < 2; ++n) {
;                         const size_t idx = (size_t)row * ldc + u.pn * BM + bj * HALF + wc * 32 + 8 * fq + 4 * n;
;                         const f32x4 b = *(const f32x4*)(base + idx);
;                         const f32x4 v = b + acc[ai][bj][m][n] * alpha;
;                         *(f32x4*)(out + idx) = v;
;                         if (NORM) { u32x2 w; w.x = pk2(v[0], v[1]); w.y = pk2(v[2], v[3]); *(u32x2*)(xb + idx) = w; sq += (v[0] * v[0] + v[1] * v[1]) + (v[2] * v[2] + v[3] * v[3]); }
;                     }
;                 if (NORM) { sq = xor16_sum(sq); sq = xor32_sum(sq); if (fq == 0) __hip_atomic_fetch_add(ss + row, sq, __ATOMIC_RELAXED, __HIP_MEMORY_SCOPE_AGENT); }
.LBB0_429:
	s_or_b64 exec, exec, s[12:13]
	v_or_b32_e32 v80, 48, v148
	v_ashrrev_i32_e32 v81, 31, v80
	v_lshlrev_b64 v[82:83], 11, v[80:81]
	v_lshl_add_u64 v[86:87], v[82:83], 0, v[146:147]
	v_lshlrev_b64 v[88:89], 2, v[86:87]
	v_lshl_add_u64 v[90:91], s[52:53], 0, v[88:89]
	s_nop 0
	v_lshlrev_b64 v[86:87], 1, v[86:87]
	s_nop 0
	s_waitcnt vmcnt(30)
	v_pk_fma_f32 v[78:79], v[78:79], 0.5, v[218:219] op_sel_hi:[1,0,1]
	v_pk_fma_f32 v[76:77], v[76:77], 0.5, v[216:217] op_sel_hi:[1,0,1]
	v_lshl_add_u64 v[82:83], s[30:31], 0, v[88:89]
	global_store_dwordx4 v[82:83], v[76:79], off
	v_cvt_pk_bf16_f32 v240, v76, v77
	v_cvt_pk_bf16_f32 v241, v78, v79
	v_mul_f32_e32 v77, v77, v77
	v_lshl_add_u64 v[88:89], s[40:41], 0, v[86:87]
	v_fmac_f32_e32 v77, v76, v76
	v_mul_f32_e32 v76, v79, v79
	s_nop 0
	v_fmac_f32_e32 v76, v78, v78
	v_add_f32_e32 v84, v77, v76
	s_nop 0
	s_nop 0
	v_pk_fma_f32 v[74:75], v[74:75], 0.5, v[222:223] op_sel_hi:[1,0,1]
	v_pk_fma_f32 v[72:73], v[72:73], 0.5, v[220:221] op_sel_hi:[1,0,1]
	global_store_dwordx4 v[82:83], v[72:75], off offset:16
	v_cvt_pk_bf16_f32 v242, v72, v73
	v_or_b32_e32 v78, 8, v86
	v_mul_f32_e32 v73, v73, v73
	v_mov_b32_e32 v79, v87
	v_fmac_f32_e32 v73, v72, v72
	v_mul_f32_e32 v72, v75, v75
	v_cvt_pk_bf16_f32 v243, v74, v75
	v_lshl_add_u64 v[78:79], s[40:41], 0, v[78:79]
	v_fmac_f32_e32 v72, v74, v74
	global_store_dwordx4 v[78:79], v[240:243], off offset:-8
	v_add_f32_e32 v72, v73, v72
	v_add_f32_e32 v76, v84, v72
	s_nop 0
	s_nop 0
	v_pk_fma_f32 v[70:71], v[70:71], 0.5, v[226:227] op_sel_hi:[1,0,1]
	v_pk_fma_f32 v[68:69], v[68:69], 0.5, v[224:225] op_sel_hi:[1,0,1]
	global_store_dwordx4 v[82:83], v[68:71], off offset:512
	v_cvt_pk_bf16_f32 v240, v68, v69
	v_or_b32_e32 v74, 0x100, v86
	v_mul_f32_e32 v69, v69, v69
	v_mov_b32_e32 v75, v87
	v_fmac_f32_e32 v69, v68, v68
	v_mul_f32_e32 v68, v71, v71
	v_cvt_pk_bf16_f32 v241, v70, v71
	v_lshl_add_u64 v[74:75], s[40:41], 0, v[74:75]
	v_fmac_f32_e32 v68, v70, v70
	s_nop 0
	v_add_f32_e32 v68, v69, v68
	v_add_f32_e32 v72, v76, v68
	s_nop 0
	v_or_b32_e32 v86, 0x108, v86
	s_nop 0
	v_pk_fma_f32 v[66:67], v[66:67], 0.5, v[236:237] op_sel_hi:[1,0,1]
	v_pk_fma_f32 v[64:65], v[64:65], 0.5, v[234:235] op_sel_hi:[1,0,1]
	v_mov_b32_e32 v230, 0x160000
	v_lshl_add_u64 v[228:229], v[232:233], 0, v[230:231]
	global_load_dwordx4 v[216:219], v[228:229], off nt
	global_load_dwordx4 v[220:223], v[228:229], off offset:16 nt
	global_load_dwordx4 v[224:227], v[228:229], off offset:512 nt
	global_load_dwordx4 v[234:237], v[228:229], off offset:528 nt
	global_store_dwordx4 v[82:83], v[64:67], off offset:528
	v_cvt_pk_bf16_f32 v242, v64, v65
	v_cvt_pk_bf16_f32 v243, v66, v67
	v_mul_f32_e32 v65, v65, v65
	v_fmac_f32_e32 v65, v64, v64
	v_mul_f32_e32 v64, v67, v67
	v_fmac_f32_e32 v64, v66, v66
	v_add_f32_e32 v64, v65, v64
	v_add_f32_e32 v64, v72, v64
	v_mov_b32_e32 v65, v64
	s_nop 1
	v_permlane16_swap_b32 v64, v65
	v_lshl_add_u64 v[70:71], s[40:41], 0, v[86:87]
	v_add_f32_e32 v64, v64, v65
	v_mov_b32_e32 v65, v64
	global_store_dwordx4 v[70:71], v[240:243], off offset:-8
	s_nop 1
	v_permlane32_swap_b32 v64, v65
	s_and_saveexec_b64 s[12:13], s[2:3]
	s_cbranch_execz .LBB0_431
	v_lshl_add_u64 v[66:67], v[80:81], 2, s[90:91]
	v_add_f32_e32 v64, v64, v65
	global_atomic_add_f32 v[66:67], v64, off
.LBB0_431:
	s_or_b64 exec, exec, s[12:13]
	v_add_u32_e32 v64, 0x80, v148
	v_ashrrev_i32_e32 v65, 31, v64
	v_lshlrev_b64 v[66:67], 11, v[64:65]
	v_lshl_add_u64 v[70:71], v[66:67], 0, v[146:147]
	v_lshlrev_b64 v[72:73], 2, v[70:71]
	v_lshl_add_u64 v[74:75], s[52:53], 0, v[72:73]
	s_nop 0
	v_lshlrev_b64 v[70:71], 1, v[70:71]
	s_nop 0
	s_waitcnt vmcnt(32)
	v_pk_fma_f32 v[62:63], v[62:63], 0.5, v[166:167] op_sel_hi:[1,0,1]
	v_pk_fma_f32 v[60:61], v[60:61], 0.5, v[164:165] op_sel_hi:[1,0,1]
	v_lshl_add_u64 v[66:67], s[30:31], 0, v[72:73]
	global_store_dwordx4 v[66:67], v[60:63], off
	v_cvt_pk_bf16_f32 v240, v60, v61
	v_cvt_pk_bf16_f32 v241, v62, v63
	v_mul_f32_e32 v61, v61, v61
	v_lshl_add_u64 v[72:73], s[40:41], 0, v[70:71]
	v_fmac_f32_e32 v61, v60, v60
	v_mul_f32_e32 v60, v63, v63
	s_nop 0
	v_fmac_f32_e32 v60, v62, v62
	v_add_f32_e32 v68, v61, v60
	s_nop 0
	s_nop 0
	v_pk_fma_f32 v[58:59], v[58:59], 0.5, v[170:171] op_sel_hi:[1,0,1]
	v_pk_fma_f32 v[56:57], v[56:57], 0.5, v[168:169] op_sel_hi:[1,0,1]
	global_store_dwordx4 v[66:67], v[56:59], off offset:16
	v_cvt_pk_bf16_f32 v242, v56, v57
	v_or_b32_e32 v62, 8, v70
	v_mul_f32_e32 v57, v57, v57
	v_mov_b32_e32 v63, v71
	v_fmac_f32_e32 v57, v56, v56
	v_mul_f32_e32 v56, v59, v59
	v_cvt_pk_bf16_f32 v243, v58, v59
	v_lshl_add_u64 v[62:63], s[40:41], 0, v[62:63]
	v_fmac_f32_e32 v56, v58, v58
	global_store_dwordx4 v[62:63], v[240:243], off offset:-8
	v_add_f32_e32 v56, v57, v56
	v_add_f32_e32 v60, v68, v56
	s_nop 0
	s_nop 0
	v_pk_fma_f32 v[54:55], v[54:55], 0.5, v[174:175] op_sel_hi:[1,0,1]
	v_pk_fma_f32 v[52:53], v[52:53], 0.5, v[172:173] op_sel_hi:[1,0,1]
	global_store_dwordx4 v[66:67], v[52:55], off offset:512
	v_cvt_pk_bf16_f32 v240, v52, v53
	v_or_b32_e32 v58, 0x100, v70
	v_mul_f32_e32 v53, v53, v53
	v_mov_b32_e32 v59, v71
	v_fmac_f32_e32 v53, v52, v52
	v_mul_f32_e32 v52, v55, v55
	v_cvt_pk_bf16_f32 v241, v54, v55
	v_lshl_add_u64 v[58:59], s[40:41], 0, v[58:59]
	v_fmac_f32_e32 v52, v54, v54
	s_nop 0
	v_add_f32_e32 v52, v53, v52
	v_add_f32_e32 v56, v60, v52
	s_nop 0
	v_or_b32_e32 v70, 0x108, v70
	s_nop 0
	v_pk_fma_f32 v[50:51], v[50:51], 0.5, v[178:179] op_sel_hi:[1,0,1]
	v_pk_fma_f32 v[48:49], v[48:49], 0.5, v[176:177] op_sel_hi:[1,0,1]
	global_store_dwordx4 v[66:67], v[48:51], off offset:528
	v_cvt_pk_bf16_f32 v242, v48, v49
	v_cvt_pk_bf16_f32 v243, v50, v51
	v_mul_f32_e32 v49, v49, v49
	v_fmac_f32_e32 v49, v48, v48
	v_mul_f32_e32 v48, v51, v51
	v_fmac_f32_e32 v48, v50, v50
	v_add_f32_e32 v48, v49, v48
	v_add_f32_e32 v48, v56, v48
	v_mov_b32_e32 v49, v48
	s_nop 1
	v_permlane16_swap_b32 v49, v48
	v_lshl_add_u64 v[54:55], s[40:41], 0, v[70:71]
	v_add_f32_e32 v48, v49, v48
	v_mov_b32_e32 v49, v48
	global_store_dwordx4 v[54:55], v[240:243], off offset:-8
	s_nop 1
	v_permlane32_swap_b32 v49, v48
	s_and_saveexec_b64 s[12:13], s[2:3]
	s_cbranch_execz .LBB0_433
	v_lshl_add_u64 v[50:51], v[64:65], 2, s[90:91]
	v_add_f32_e32 v48, v49, v48
	global_atomic_add_f32 v[50:51], v48, off
; __device__ __forceinline__ unsigned pk2(float lo, float hi) { f32x2_t v = {lo, hi}; bf16x2_t b = __builtin_convertvector(v, bf16x2_t); return __builtin_bit_cast(unsigned, b); }
; __device__ __forceinline__ float xor16_sum(float v) { float a = v, b = v; swap16(a, b); return a + b; }
; __device__ __forceinline__ float xor32_sum(float v) { float a = v, b = v; swap32(a, b); return a + b; }
;     __device__ __forceinline__ void operator()(const f32x4 (&acc)[2][2][4][2], const Unit& u, int wr, int wc, int fr, int fq) const {
;     ...
;                 const int row = row0 + ai * HALF + m * 16; float sq = 0.f;
; #pragma unroll
;                 for (int bj = 0; bj < 2; ++bj)
; #pragma unroll
;                     for (int n = 0; n < 2; ++n) {
;                         const size_t idx = (size_t)row * ldc + u.pn * BM + bj * HALF + wc * 32 + 8 * fq + 4 * n;
;                         const f32x4 b = *(const f32x4*)(base + idx);
;                         const f32x4 v = b + acc[ai][bj][m][n] * alpha;
;                         *(f32x4*)(out + idx) = v;
;                         if (NORM) { u32x2 w; w.x = pk2(v[0], v[1]); w.y = pk2(v[2], v[3]); *(u32x2*)(xb + idx) = w; sq += (v[0] * v[0] + v[1] * v[1]) + (v[2] * v[2] + v[3] * v[3]); }
;                     }
;                 if (NORM) { sq = xor16_sum(sq); sq = xor32_sum(sq); if (fq == 0) __hip_atomic_fetch_add(ss + row, sq, __ATOMIC_RELAXED, __HIP_MEMORY_SCOPE_AGENT); }
.LBB0_433:
	s_or_b64 exec, exec, s[12:13]
	v_add_u32_e32 v48, 0x90, v148
	v_ashrrev_i32_e32 v49, 31, v48
	v_lshlrev_b64 v[50:51], 11, v[48:49]
	v_lshl_add_u64 v[54:55], v[50:51], 0, v[146:147]
	v_lshlrev_b64 v[56:57], 2, v[54:55]
	v_lshl_add_u64 v[58:59], s[52:53], 0, v[56:57]
	s_nop 0
	v_lshlrev_b64 v[54:55], 1, v[54:55]
	s_nop 0
	s_waitcnt vmcnt(28)
	v_pk_fma_f32 v[46:47], v[46:47], 0.5, v[182:183] op_sel_hi:[1,0,1]
	v_pk_fma_f32 v[44:45], v[44:45], 0.5, v[180:181] op_sel_hi:[1,0,1]
	v_lshl_add_u64 v[50:51], s[30:31], 0, v[56:57]
	global_store_dwordx4 v[50:51], v[44:47], off
	v_cvt_pk_bf16_f32 v240, v44, v45
	v_cvt_pk_bf16_f32 v241, v46, v47
	v_mul_f32_e32 v45, v45, v45
	v_lshl_add_u64 v[56:57], s[40:41], 0, v[54:55]
	v_fmac_f32_e32 v45, v44, v44
	v_mul_f32_e32 v44, v47, v47
	s_nop 0
	v_fmac_f32_e32 v44, v46, v46
	v_add_f32_e32 v52, v45, v44
	s_nop 0
	s_nop 0
	v_pk_fma_f32 v[42:43], v[42:43], 0.5, v[190:191] op_sel_hi:[1,0,1]
	v_pk_fma_f32 v[40:41], v[40:41], 0.5, v[188:189] op_sel_hi:[1,0,1]
	global_store_dwordx4 v[50:51], v[40:43], off offset:16
	v_cvt_pk_bf16_f32 v242, v40, v41
	v_or_b32_e32 v46, 8, v54
	v_mul_f32_e32 v41, v41, v41
	v_mov_b32_e32 v47, v55
	v_fmac_f32_e32 v41, v40, v40
	v_mul_f32_e32 v40, v43, v43
	v_cvt_pk_bf16_f32 v243, v42, v43
	v_lshl_add_u64 v[46:47], s[40:41], 0, v[46:47]
	v_fmac_f32_e32 v40, v42, v42
	global_store_dwordx4 v[46:47], v[240:243], off offset:-8
	v_add_f32_e32 v40, v41, v40
	v_add_f32_e32 v44, v52, v40
	s_nop 0
	s_nop 0
	v_pk_fma_f32 v[38:39], v[38:39], 0.5, v[194:195] op_sel_hi:[1,0,1]
	v_pk_fma_f32 v[36:37], v[36:37], 0.5, v[192:193] op_sel_hi:[1,0,1]
	global_store_dwordx4 v[50:51], v[36:39], off offset:512
	v_cvt_pk_bf16_f32 v240, v36, v37
	v_or_b32_e32 v42, 0x100, v54
	v_mul_f32_e32 v37, v37, v37
	v_mov_b32_e32 v43, v55
	v_fmac_f32_e32 v37, v36, v36
	v_mul_f32_e32 v36, v39, v39
	v_cvt_pk_bf16_f32 v241, v38, v39
	v_lshl_add_u64 v[42:43], s[40:41], 0, v[42:43]
	v_fmac_f32_e32 v36, v38, v38
	s_nop 0
	v_add_f32_e32 v36, v37, v36
	v_add_f32_e32 v40, v44, v36
	s_nop 0
	v_or_b32_e32 v54, 0x108, v54
	s_nop 0
	v_pk_fma_f32 v[34:35], v[34:35], 0.5, v[198:199] op_sel_hi:[1,0,1]
	v_pk_fma_f32 v[32:33], v[32:33], 0.5, v[196:197] op_sel_hi:[1,0,1]
	global_store_dwordx4 v[50:51], v[32:35], off offset:528
	v_cvt_pk_bf16_f32 v242, v32, v33
	v_cvt_pk_bf16_f32 v243, v34, v35
	v_mul_f32_e32 v33, v33, v33
	v_fmac_f32_e32 v33, v32, v32
	v_mul_f32_e32 v32, v35, v35
	v_fmac_f32_e32 v32, v34, v34
	v_add_f32_e32 v32, v33, v32
	v_add_f32_e32 v32, v40, v32
	v_mov_b32_e32 v33, v32
	s_nop 1
	v_permlane16_swap_b32 v32, v33
	v_lshl_add_u64 v[38:39], s[40:41], 0, v[54:55]
	v_add_f32_e32 v32, v32, v33
	v_mov_b32_e32 v33, v32
	global_store_dwordx4 v[38:39], v[240:243], off offset:-8
	s_nop 1
	v_permlane32_swap_b32 v32, v33
	s_and_saveexec_b64 s[12:13], s[2:3]
	s_cbranch_execz .LBB0_435
	v_lshl_add_u64 v[34:35], v[48:49], 2, s[90:91]
	v_add_f32_e32 v32, v32, v33
	global_atomic_add_f32 v[34:35], v32, off
; __device__ __forceinline__ unsigned pk2(float lo, float hi) { f32x2_t v = {lo, hi}; bf16x2_t b = __builtin_convertvector(v, bf16x2_t); return __builtin_bit_cast(unsigned, b); }
; __device__ __forceinline__ float xor16_sum(float v) { float a = v, b = v; swap16(a, b); return a + b; }
; __device__ __forceinline__ float xor32_sum(float v) { float a = v, b = v; swap32(a, b); return a + b; }
;     __device__ __forceinline__ void operator()(const f32x4 (&acc)[2][2][4][2], const Unit& u, int wr, int wc, int fr, int fq) const {
;     ...
;                 const int row = row0 + ai * HALF + m * 16; float sq = 0.f;
; #pragma unroll
;                 for (int bj = 0; bj < 2; ++bj)
; #pragma unroll
;                     for (int n = 0; n < 2; ++n) {
;                         const size_t idx = (size_t)row * ldc + u.pn * BM + bj * HALF + wc * 32 + 8 * fq + 4 * n;
;                         const f32x4 b = *(const f32x4*)(base + idx);
;                         const f32x4 v = b + acc[ai][bj][m][n] * alpha;
;                         *(f32x4*)(out + idx) = v;
;                         if (NORM) { u32x2 w; w.x = pk2(v[0], v[1]); w.y = pk2(v[2], v[3]); *(u32x2*)(xb + idx) = w; sq += (v[0] * v[0] + v[1] * v[1]) + (v[2] * v[2] + v[3] * v[3]); }
;                     }
;                 if (NORM) { sq = xor16_sum(sq); sq = xor32_sum(sq); if (fq == 0) __hip_atomic_fetch_add(ss + row, sq, __ATOMIC_RELAXED, __HIP_MEMORY_SCOPE_AGENT); }
.LBB0_435:
	s_or_b64 exec, exec, s[12:13]
	v_add_u32_e32 v32, 0xa0, v148
	v_ashrrev_i32_e32 v33, 31, v32
	v_lshlrev_b64 v[34:35], 11, v[32:33]
	v_lshl_add_u64 v[38:39], v[34:35], 0, v[146:147]
	v_lshlrev_b64 v[40:41], 2, v[38:39]
	v_lshl_add_u64 v[42:43], s[52:53], 0, v[40:41]
	s_nop 0
	v_lshlrev_b64 v[38:39], 1, v[38:39]
	s_nop 0
	s_waitcnt vmcnt(24)
	v_pk_fma_f32 v[30:31], v[30:31], 0.5, v[202:203] op_sel_hi:[1,0,1]
	v_pk_fma_f32 v[28:29], v[28:29], 0.5, v[200:201] op_sel_hi:[1,0,1]
	v_lshl_add_u64 v[34:35], s[30:31], 0, v[40:41]
	global_store_dwordx4 v[34:35], v[28:31], off
	v_cvt_pk_bf16_f32 v240, v28, v29
	v_cvt_pk_bf16_f32 v241, v30, v31
	v_mul_f32_e32 v29, v29, v29
	v_lshl_add_u64 v[40:41], s[40:41], 0, v[38:39]
	v_fmac_f32_e32 v29, v28, v28
	v_mul_f32_e32 v28, v31, v31
	s_nop 0
	v_fmac_f32_e32 v28, v30, v30
	v_add_f32_e32 v36, v29, v28
	s_nop 0
	s_nop 0
	v_pk_fma_f32 v[26:27], v[26:27], 0.5, v[206:207] op_sel_hi:[1,0,1]
	v_pk_fma_f32 v[24:25], v[24:25], 0.5, v[204:205] op_sel_hi:[1,0,1]
	global_store_dwordx4 v[34:35], v[24:27], off offset:16
	v_cvt_pk_bf16_f32 v242, v24, v25
	v_or_b32_e32 v30, 8, v38
	v_mul_f32_e32 v25, v25, v25
	v_mov_b32_e32 v31, v39
	v_fmac_f32_e32 v25, v24, v24
	v_mul_f32_e32 v24, v27, v27
	v_cvt_pk_bf16_f32 v243, v26, v27
	v_lshl_add_u64 v[30:31], s[40:41], 0, v[30:31]
	v_fmac_f32_e32 v24, v26, v26
	global_store_dwordx4 v[30:31], v[240:243], off offset:-8
	v_add_f32_e32 v24, v25, v24
	v_add_f32_e32 v28, v36, v24
	s_nop 0
	s_nop 0
	v_pk_fma_f32 v[22:23], v[22:23], 0.5, v[210:211] op_sel_hi:[1,0,1]
	v_pk_fma_f32 v[20:21], v[20:21], 0.5, v[208:209] op_sel_hi:[1,0,1]
	global_store_dwordx4 v[34:35], v[20:23], off offset:512
	v_cvt_pk_bf16_f32 v240, v20, v21
	v_or_b32_e32 v26, 0x100, v38
	v_mul_f32_e32 v21, v21, v21
	v_mov_b32_e32 v27, v39
	v_fmac_f32_e32 v21, v20, v20
	v_mul_f32_e32 v20, v23, v23
	v_cvt_pk_bf16_f32 v241, v22, v23
	v_lshl_add_u64 v[26:27], s[40:41], 0, v[26:27]
	v_fmac_f32_e32 v20, v22, v22
	s_nop 0
	v_add_f32_e32 v20, v21, v20
	v_add_f32_e32 v24, v28, v20
	s_nop 0
	v_or_b32_e32 v38, 0x108, v38
	s_nop 0
	v_pk_fma_f32 v[18:19], v[18:19], 0.5, v[214:215] op_sel_hi:[1,0,1]
	v_pk_fma_f32 v[16:17], v[16:17], 0.5, v[212:213] op_sel_hi:[1,0,1]
	global_store_dwordx4 v[34:35], v[16:19], off offset:528
	v_cvt_pk_bf16_f32 v242, v16, v17
	v_cvt_pk_bf16_f32 v243, v18, v19
	v_mul_f32_e32 v17, v17, v17
	v_fmac_f32_e32 v17, v16, v16
	v_mul_f32_e32 v16, v19, v19
	v_fmac_f32_e32 v16, v18, v18
	v_add_f32_e32 v16, v17, v16
	v_add_f32_e32 v16, v24, v16
	v_mov_b32_e32 v17, v16
	s_nop 1
	v_permlane16_swap_b32 v16, v17
	v_lshl_add_u64 v[22:23], s[40:41], 0, v[38:39]
	v_add_f32_e32 v16, v16, v17
	v_mov_b32_e32 v17, v16
	global_store_dwordx4 v[22:23], v[240:243], off offset:-8
	s_nop 1
	v_permlane32_swap_b32 v16, v17
	s_and_saveexec_b64 s[12:13], s[2:3]
	s_cbranch_execz .LBB0_437
	v_lshl_add_u64 v[18:19], v[32:33], 2, s[90:91]
	v_add_f32_e32 v16, v16, v17
	global_atomic_add_f32 v[18:19], v16, off
.LBB0_437:
	s_or_b64 exec, exec, s[12:13]
	v_add_u32_e32 v16, 0xb0, v148
	v_ashrrev_i32_e32 v17, 31, v16
	v_lshlrev_b64 v[18:19], 11, v[16:17]
	v_lshl_add_u64 v[22:23], v[18:19], 0, v[146:147]
	v_lshlrev_b64 v[24:25], 2, v[22:23]
	v_lshl_add_u64 v[26:27], s[52:53], 0, v[24:25]
	s_nop 0
	v_lshlrev_b64 v[22:23], 1, v[22:23]
	s_nop 0
	s_waitcnt vmcnt(20)
	v_pk_fma_f32 v[14:15], v[14:15], 0.5, v[218:219] op_sel_hi:[1,0,1]
	v_pk_fma_f32 v[12:13], v[12:13], 0.5, v[216:217] op_sel_hi:[1,0,1]
	v_lshl_add_u64 v[18:19], s[30:31], 0, v[24:25]
	global_store_dwordx4 v[18:19], v[12:15], off
	v_cvt_pk_bf16_f32 v240, v12, v13
	v_cvt_pk_bf16_f32 v241, v14, v15
	v_mul_f32_e32 v13, v13, v13
	v_lshl_add_u64 v[24:25], s[40:41], 0, v[22:23]
	v_fmac_f32_e32 v13, v12, v12
	v_mul_f32_e32 v12, v15, v15
	s_nop 0
	v_fmac_f32_e32 v12, v14, v14
	v_add_f32_e32 v20, v13, v12
	s_nop 0
	s_nop 0
	v_pk_fma_f32 v[10:11], v[10:11], 0.5, v[222:223] op_sel_hi:[1,0,1]
	v_pk_fma_f32 v[8:9], v[8:9], 0.5, v[220:221] op_sel_hi:[1,0,1]
	global_store_dwordx4 v[18:19], v[8:11], off offset:16
	v_cvt_pk_bf16_f32 v242, v8, v9
	v_or_b32_e32 v14, 8, v22
	v_mul_f32_e32 v9, v9, v9
	v_mov_b32_e32 v15, v23
	v_fmac_f32_e32 v9, v8, v8
	v_mul_f32_e32 v8, v11, v11
	v_cvt_pk_bf16_f32 v243, v10, v11
	v_lshl_add_u64 v[14:15], s[40:41], 0, v[14:15]
	v_fmac_f32_e32 v8, v10, v10
	global_store_dwordx4 v[14:15], v[240:243], off offset:-8
	v_add_f32_e32 v8, v9, v8
	v_add_f32_e32 v12, v20, v8
	s_nop 0
	s_nop 0
	v_pk_fma_f32 v[6:7], v[6:7], 0.5, v[226:227] op_sel_hi:[1,0,1]
	v_pk_fma_f32 v[4:5], v[4:5], 0.5, v[224:225] op_sel_hi:[1,0,1]
	global_store_dwordx4 v[18:19], v[4:7], off offset:512
	v_cvt_pk_bf16_f32 v240, v4, v5
	v_or_b32_e32 v10, 0x100, v22
	v_mul_f32_e32 v5, v5, v5
	v_mov_b32_e32 v11, v23
	v_fmac_f32_e32 v5, v4, v4
	v_mul_f32_e32 v4, v7, v7
	v_cvt_pk_bf16_f32 v241, v6, v7
	v_lshl_add_u64 v[10:11], s[40:41], 0, v[10:11]
	v_fmac_f32_e32 v4, v6, v6
	s_nop 0
	v_add_f32_e32 v4, v5, v4
	v_add_f32_e32 v8, v12, v4
	s_nop 0
	v_or_b32_e32 v22, 0x108, v22
	s_nop 0
	v_pk_fma_f32 v[2:3], v[2:3], 0.5, v[236:237] op_sel_hi:[1,0,1]
	v_pk_fma_f32 v[0:1], v[0:1], 0.5, v[234:235] op_sel_hi:[1,0,1]
	global_store_dwordx4 v[18:19], v[0:3], off offset:528
	v_cvt_pk_bf16_f32 v242, v0, v1
	v_cvt_pk_bf16_f32 v243, v2, v3
	v_mul_f32_e32 v1, v1, v1
	v_fmac_f32_e32 v1, v0, v0
	v_mul_f32_e32 v0, v3, v3
	v_fmac_f32_e32 v0, v2, v2
	v_add_f32_e32 v0, v1, v0
	v_add_f32_e32 v0, v8, v0
	v_mov_b32_e32 v1, v0
	s_nop 1
	v_permlane16_swap_b32 v0, v1
	v_lshl_add_u64 v[6:7], s[40:41], 0, v[22:23]
	v_add_f32_e32 v0, v0, v1
	v_mov_b32_e32 v1, v0
	global_store_dwordx4 v[6:7], v[240:243], off offset:-8
	s_nop 1
	v_permlane32_swap_b32 v0, v1
	s_and_saveexec_b64 s[12:13], s[2:3]
	s_cbranch_execz .LBB0_439
	v_lshl_add_u64 v[2:3], v[16:17], 2, s[90:91]
	v_add_f32_e32 v0, v0, v1
	global_atomic_add_f32 v[2:3], v0, off

; __device__ __forceinline__ unsigned pk2(float lo, float hi) { f32x2_t v = {lo, hi}; bf16x2_t b = __builtin_convertvector(v, bf16x2_t); return __builtin_bit_cast(unsigned, b); }
; __device__ __forceinline__ float xor16_sum(float v) { float a = v, b = v; swap16(a, b); return a + b; }
; __device__ __forceinline__ float xor32_sum(float v) { float a = v, b = v; swap32(a, b); return a + b; }
;     __device__ __forceinline__ void operator()(const f32x4 (&acc)[2][2][4][2], const Unit& u, int wr, int wc, int fr, int fq) const {
;     ...
;                 const int row = row0 + ai * HALF + m * 16; float sq = 0.f;
; #pragma unroll
;                 for (int bj = 0; bj < 2; ++bj)
; #pragma unroll
;                     for (int n = 0; n < 2; ++n) {
;                         const size_t idx = (size_t)row * ldc + u.pn * BM + bj * HALF + wc * 32 + 8 * fq + 4 * n;
;                         const f32x4 b = *(const f32x4*)(base + idx);
;                         const f32x4 v = b + acc[ai][bj][m][n] * alpha;
;                         *(f32x4*)(out + idx) = v;
;                         if (NORM) { u32x2 w; w.x = pk2(v[0], v[1]); w.y = pk2(v[2], v[3]); *(u32x2*)(xb + idx) = w; sq += (v[0] * v[0] + v[1] * v[1]) + (v[2] * v[2] + v[3] * v[3]); }
;                     }
;                 if (NORM) { sq = xor16_sum(sq); sq = xor32_sum(sq); if (fq == 0) __hip_atomic_fetch_add(ss + row, sq, __ATOMIC_RELAXED, __HIP_MEMORY_SCOPE_AGENT); }
.LBB0_1208:
	v_lshl_add_u32 v148, s12, 8, v137
	s_lshl_b32 s12, s44, 8
	s_ashr_i32 s13, s12, 31
	v_ashrrev_i32_e32 v149, 31, v148
	v_mov_b32_e32 v147, s13
	v_or_b32_e32 v146, s12, v136
	v_lshlrev_b64 v[154:155], 11, v[148:149]
	v_lshl_add_u64 v[158:159], v[154:155], 0, v[146:147]
	v_lshl_add_u64 v[160:161], v[158:159], 2, s[30:31]
	v_mov_b32_e32 v232, v160
	v_mov_b32_e32 v233, v161
	v_mov_b32_e32 v231, 0
	v_mov_b32_e32 v230, 0x0
	v_lshl_add_u64 v[228:229], v[232:233], 0, v[230:231]
	global_load_dwordx4 v[164:167], v[228:229], off nt
	global_load_dwordx4 v[168:171], v[228:229], off offset:16 nt
	global_load_dwordx4 v[172:175], v[228:229], off offset:512 nt
	global_load_dwordx4 v[176:179], v[228:229], off offset:528 nt
	v_mov_b32_e32 v230, 0x20000
	v_lshl_add_u64 v[228:229], v[232:233], 0, v[230:231]
	global_load_dwordx4 v[180:183], v[228:229], off nt
	global_load_dwordx4 v[188:191], v[228:229], off offset:16 nt
	global_load_dwordx4 v[192:195], v[228:229], off offset:512 nt
	global_load_dwordx4 v[196:199], v[228:229], off offset:528 nt
	v_mov_b32_e32 v230, 0x40000
	v_lshl_add_u64 v[228:229], v[232:233], 0, v[230:231]
	global_load_dwordx4 v[200:203], v[228:229], off nt
	global_load_dwordx4 v[204:207], v[228:229], off offset:16 nt
	global_load_dwordx4 v[208:211], v[228:229], off offset:512 nt
	global_load_dwordx4 v[212:215], v[228:229], off offset:528 nt
	v_mov_b32_e32 v230, 0x60000
	v_lshl_add_u64 v[228:229], v[232:233], 0, v[230:231]
	global_load_dwordx4 v[216:219], v[228:229], off nt
	global_load_dwordx4 v[220:223], v[228:229], off offset:16 nt
	global_load_dwordx4 v[224:227], v[228:229], off offset:512 nt
	global_load_dwordx4 v[234:237], v[228:229], off offset:528 nt
	s_nop 0
	v_lshlrev_b64 v[158:159], 1, v[158:159]
	v_lshl_add_u64 v[162:163], s[6:7], 0, v[158:159]
	s_nop 0
	s_waitcnt vmcnt(12)
	v_pk_add_f32 v[126:127], v[126:127], v[166:167]
	v_pk_add_f32 v[124:125], v[124:125], v[164:165]
	v_cvt_pk_bf16_f32 v241, v126, v127
	v_cvt_pk_bf16_f32 v240, v124, v125
	global_store_dwordx4 v[160:161], v[124:127], off
	s_nop 0
	s_nop 0
	v_or_b32_e32 v162, 8, v158
	v_mov_b32_e32 v163, v159
	v_lshl_add_u64 v[162:163], s[6:7], 0, v[162:163]
	v_mul_f32_e32 v125, v125, v125
	v_mul_f32_e32 v127, v127, v127
	v_fmac_f32_e32 v125, v124, v124
	v_fmac_f32_e32 v127, v126, v126
	v_add_f32_e32 v124, v125, v127
	s_nop 0
	v_pk_add_f32 v[122:123], v[122:123], v[170:171]
	v_pk_add_f32 v[120:121], v[120:121], v[168:169]
	v_cvt_pk_bf16_f32 v243, v122, v123
	v_cvt_pk_bf16_f32 v242, v120, v121
	global_store_dwordx4 v[160:161], v[120:123], off offset:16
	global_store_dwordx4 v[162:163], v[240:243], off offset:-8
	s_nop 0
	v_or_b32_e32 v162, 0x100, v158
	v_mov_b32_e32 v163, v159
	v_lshl_add_u64 v[162:163], s[6:7], 0, v[162:163]
	v_mul_f32_e32 v121, v121, v121
	v_mul_f32_e32 v123, v123, v123
	v_fmac_f32_e32 v121, v120, v120
	v_fmac_f32_e32 v123, v122, v122
	v_add_f32_e32 v120, v121, v123
	v_add_f32_e32 v120, v124, v120
	v_or_b32_e32 v158, 0x108, v158
	v_lshl_add_u64 v[158:159], s[6:7], 0, v[158:159]
	s_nop 0
	v_pk_add_f32 v[118:119], v[118:119], v[174:175]
	v_pk_add_f32 v[116:117], v[116:117], v[172:173]
	v_cvt_pk_bf16_f32 v241, v118, v119
	v_cvt_pk_bf16_f32 v240, v116, v117
	global_store_dwordx4 v[160:161], v[116:119], off offset:512
	s_nop 0
	s_nop 0
	v_mul_f32_e32 v117, v117, v117
	v_mul_f32_e32 v119, v119, v119
	v_fmac_f32_e32 v117, v116, v116
	v_fmac_f32_e32 v119, v118, v118
	v_add_f32_e32 v116, v117, v119
	v_add_f32_e32 v118, v120, v116
	s_nop 0
	v_pk_add_f32 v[114:115], v[114:115], v[178:179]
	v_pk_add_f32 v[112:113], v[112:113], v[176:177]
	v_mov_b32_e32 v230, 0x100000
	v_lshl_add_u64 v[228:229], v[232:233], 0, v[230:231]
	global_load_dwordx4 v[164:167], v[228:229], off nt
	global_load_dwordx4 v[168:171], v[228:229], off offset:16 nt
	global_load_dwordx4 v[172:175], v[228:229], off offset:512 nt
	global_load_dwordx4 v[176:179], v[228:229], off offset:528 nt
	global_store_dwordx4 v[160:161], v[112:115], off offset:528
	v_cvt_pk_bf16_f32 v242, v112, v113
	v_cvt_pk_bf16_f32 v243, v114, v115
	v_mul_f32_e32 v113, v113, v113
	v_mul_f32_e32 v115, v115, v115
	v_fmac_f32_e32 v113, v112, v112
	v_fmac_f32_e32 v115, v114, v114
	v_add_f32_e32 v112, v113, v115
	v_add_f32_e32 v112, v118, v112
	v_mov_b32_e32 v113, v112
	s_nop 1
	v_permlane16_swap_b32 v113, v112
	global_store_dwordx4 v[158:159], v[240:243], off offset:-8
	v_add_f32_e32 v112, v113, v112
	v_mov_b32_e32 v113, v112
	s_nop 1
	v_permlane32_swap_b32 v113, v112
	s_and_saveexec_b64 s[12:13], s[2:3]
	s_cbranch_execz .LBB0_1210
	v_lshl_add_u64 v[114:115], v[148:149], 2, s[8:9]
	v_add_f32_e32 v112, v113, v112
	global_atomic_add_f32 v[114:115], v112, off
; __device__ __forceinline__ unsigned pk2(float lo, float hi) { f32x2_t v = {lo, hi}; bf16x2_t b = __builtin_convertvector(v, bf16x2_t); return __builtin_bit_cast(unsigned, b); }
; __device__ __forceinline__ float xor16_sum(float v) { float a = v, b = v; swap16(a, b); return a + b; }
; __device__ __forceinline__ float xor32_sum(float v) { float a = v, b = v; swap32(a, b); return a + b; }
;     __device__ __forceinline__ void operator()(const f32x4 (&acc)[2][2][4][2], const Unit& u, int wr, int wc, int fr, int fq) const {
;     ...
;         for (int ai = 0; ai < 2; ++ai)
; #pragma unroll
;             for (int m = 0; m < 4; ++m) {
;                 const int row = row0 + ai * HALF + m * 16; float sq = 0.f;
; #pragma unroll
;                 for (int bj = 0; bj < 2; ++bj)
; #pragma unroll
;                     for (int n = 0; n < 2; ++n) {
;                         const size_t idx = (size_t)row * ldc + u.pn * BM + bj * HALF + wc * 32 + 8 * fq + 4 * n;
;                         const f32x4 b = *(const f32x4*)(base + idx);
;                         const f32x4 v = b + acc[ai][bj][m][n] * alpha;
;                         *(f32x4*)(out + idx) = v;
;                         if (NORM) { u32x2 w; w.x = pk2(v[0], v[1]); w.y = pk2(v[2], v[3]); *(u32x2*)(xb + idx) = w; sq += (v[0] * v[0] + v[1] * v[1]) + (v[2] * v[2] + v[3] * v[3]); }
;                     }
;                 if (NORM) { sq = xor16_sum(sq); sq = xor32_sum(sq); if (fq == 0) __hip_atomic_fetch_add(ss + row, sq, __ATOMIC_RELAXED, __HIP_MEMORY_SCOPE_AGENT); }
.LBB0_1210:
	s_or_b64 exec, exec, s[12:13]
	v_or_b32_e32 v112, 16, v148
	v_ashrrev_i32_e32 v113, 31, v112
	v_lshlrev_b64 v[114:115], 11, v[112:113]
	v_lshl_add_u64 v[118:119], v[114:115], 0, v[146:147]
	v_lshl_add_u64 v[120:121], v[118:119], 2, s[30:31]
	s_nop 0
	v_lshlrev_b64 v[118:119], 1, v[118:119]
	v_lshl_add_u64 v[122:123], s[6:7], 0, v[118:119]
	s_nop 0
	s_waitcnt vmcnt(18)
	v_pk_add_f32 v[110:111], v[110:111], v[182:183]
	v_pk_add_f32 v[108:109], v[108:109], v[180:181]
	v_cvt_pk_bf16_f32 v241, v110, v111
	v_cvt_pk_bf16_f32 v240, v108, v109
	global_store_dwordx4 v[120:121], v[108:111], off
	s_nop 0
	s_nop 0
	v_or_b32_e32 v122, 8, v118
	v_mov_b32_e32 v123, v119
	v_lshl_add_u64 v[122:123], s[6:7], 0, v[122:123]
	v_mul_f32_e32 v109, v109, v109
	v_mul_f32_e32 v111, v111, v111
	v_fmac_f32_e32 v109, v108, v108
	v_fmac_f32_e32 v111, v110, v110
	v_add_f32_e32 v108, v109, v111
	s_nop 0
	v_pk_add_f32 v[106:107], v[106:107], v[190:191]
	v_pk_add_f32 v[104:105], v[104:105], v[188:189]
	v_cvt_pk_bf16_f32 v243, v106, v107
	v_cvt_pk_bf16_f32 v242, v104, v105
	global_store_dwordx4 v[120:121], v[104:107], off offset:16
	global_store_dwordx4 v[122:123], v[240:243], off offset:-8
	s_nop 0
	v_or_b32_e32 v122, 0x100, v118
	v_mov_b32_e32 v123, v119
	v_lshl_add_u64 v[122:123], s[6:7], 0, v[122:123]
	v_mul_f32_e32 v105, v105, v105
	v_mul_f32_e32 v107, v107, v107
	v_fmac_f32_e32 v105, v104, v104
	v_fmac_f32_e32 v107, v106, v106
	v_add_f32_e32 v104, v105, v107
	v_add_f32_e32 v104, v108, v104
	v_or_b32_e32 v118, 0x108, v118
	v_lshl_add_u64 v[118:119], s[6:7], 0, v[118:119]
	s_nop 0
	v_pk_add_f32 v[102:103], v[102:103], v[194:195]
	v_pk_add_f32 v[100:101], v[100:101], v[192:193]
	v_cvt_pk_bf16_f32 v241, v102, v103
	v_cvt_pk_bf16_f32 v240, v100, v101
	global_store_dwordx4 v[120:121], v[100:103], off offset:512
	s_nop 0
	s_nop 0
	v_mul_f32_e32 v101, v101, v101
	v_mul_f32_e32 v103, v103, v103
	v_fmac_f32_e32 v101, v100, v100
	v_fmac_f32_e32 v103, v102, v102
	v_add_f32_e32 v100, v101, v103
	v_add_f32_e32 v102, v104, v100
	s_nop 0
	v_pk_add_f32 v[98:99], v[98:99], v[198:199]
	v_pk_add_f32 v[96:97], v[96:97], v[196:197]
	v_mov_b32_e32 v230, 0x120000
	v_lshl_add_u64 v[228:229], v[232:233], 0, v[230:231]
	global_load_dwordx4 v[180:183], v[228:229], off nt
	global_load_dwordx4 v[188:191], v[228:229], off offset:16 nt
	global_load_dwordx4 v[192:195], v[228:229], off offset:512 nt
	global_load_dwordx4 v[196:199], v[228:229], off offset:528 nt
	global_store_dwordx4 v[120:121], v[96:99], off offset:528
	v_cvt_pk_bf16_f32 v242, v96, v97
	v_cvt_pk_bf16_f32 v243, v98, v99
	v_mul_f32_e32 v97, v97, v97
	v_mul_f32_e32 v99, v99, v99
	v_fmac_f32_e32 v97, v96, v96
	v_fmac_f32_e32 v99, v98, v98
	v_add_f32_e32 v96, v97, v99
	v_add_f32_e32 v96, v102, v96
	v_mov_b32_e32 v97, v96
	s_nop 1
	v_permlane16_swap_b32 v96, v97
	global_store_dwordx4 v[118:119], v[240:243], off offset:-8
	v_add_f32_e32 v96, v96, v97
	v_mov_b32_e32 v97, v96
	s_nop 1
	v_permlane32_swap_b32 v96, v97
	s_and_saveexec_b64 s[12:13], s[2:3]
	s_cbranch_execz .LBB0_1212
	v_lshl_add_u64 v[98:99], v[112:113], 2, s[8:9]
	v_add_f32_e32 v96, v96, v97
	global_atomic_add_f32 v[98:99], v96, off
.LBB0_1212:
	s_or_b64 exec, exec, s[12:13]
	v_or_b32_e32 v96, 32, v148
	v_ashrrev_i32_e32 v97, 31, v96
	v_lshlrev_b64 v[98:99], 11, v[96:97]
	v_lshl_add_u64 v[102:103], v[98:99], 0, v[146:147]
	v_lshl_add_u64 v[104:105], v[102:103], 2, s[30:31]
	s_nop 0
	v_lshlrev_b64 v[102:103], 1, v[102:103]
	v_lshl_add_u64 v[106:107], s[6:7], 0, v[102:103]
	s_nop 0
	s_waitcnt vmcnt(24)
	v_pk_add_f32 v[94:95], v[94:95], v[202:203]
	v_pk_add_f32 v[92:93], v[92:93], v[200:201]
	v_cvt_pk_bf16_f32 v241, v94, v95
	v_cvt_pk_bf16_f32 v240, v92, v93
	global_store_dwordx4 v[104:105], v[92:95], off
	s_nop 0
	s_nop 0
	v_or_b32_e32 v106, 8, v102
	v_mov_b32_e32 v107, v103
	v_lshl_add_u64 v[106:107], s[6:7], 0, v[106:107]
	v_mul_f32_e32 v93, v93, v93
	v_mul_f32_e32 v95, v95, v95
	v_fmac_f32_e32 v93, v92, v92
	v_fmac_f32_e32 v95, v94, v94
	v_add_f32_e32 v92, v93, v95
	s_nop 0
	v_pk_add_f32 v[90:91], v[90:91], v[206:207]
	v_pk_add_f32 v[88:89], v[88:89], v[204:205]
	v_cvt_pk_bf16_f32 v243, v90, v91
	v_cvt_pk_bf16_f32 v242, v88, v89
	global_store_dwordx4 v[104:105], v[88:91], off offset:16
	global_store_dwordx4 v[106:107], v[240:243], off offset:-8
	s_nop 0
	v_or_b32_e32 v106, 0x100, v102
	v_mov_b32_e32 v107, v103
	v_lshl_add_u64 v[106:107], s[6:7], 0, v[106:107]
	v_mul_f32_e32 v89, v89, v89
	v_mul_f32_e32 v91, v91, v91
	v_fmac_f32_e32 v89, v88, v88
	v_fmac_f32_e32 v91, v90, v90
	v_add_f32_e32 v88, v89, v91
	v_add_f32_e32 v88, v92, v88
	v_or_b32_e32 v102, 0x108, v102
	v_lshl_add_u64 v[102:103], s[6:7], 0, v[102:103]
	s_nop 0
	v_pk_add_f32 v[86:87], v[86:87], v[210:211]
	v_pk_add_f32 v[84:85], v[84:85], v[208:209]
	v_cvt_pk_bf16_f32 v241, v86, v87
	v_cvt_pk_bf16_f32 v240, v84, v85
	global_store_dwordx4 v[104:105], v[84:87], off offset:512
	s_nop 0
	s_nop 0
	v_mul_f32_e32 v85, v85, v85
	v_mul_f32_e32 v87, v87, v87
	v_fmac_f32_e32 v85, v84, v84
	v_fmac_f32_e32 v87, v86, v86
	v_add_f32_e32 v84, v85, v87
	v_add_f32_e32 v86, v88, v84
	s_nop 0
	v_pk_add_f32 v[82:83], v[82:83], v[214:215]
	v_pk_add_f32 v[80:81], v[80:81], v[212:213]
	v_mov_b32_e32 v230, 0x140000
	v_lshl_add_u64 v[228:229], v[232:233], 0, v[230:231]
	global_load_dwordx4 v[200:203], v[228:229], off nt
	global_load_dwordx4 v[204:207], v[228:229], off offset:16 nt
	global_load_dwordx4 v[208:211], v[228:229], off offset:512 nt
	global_load_dwordx4 v[212:215], v[228:229], off offset:528 nt
	global_store_dwordx4 v[104:105], v[80:83], off offset:528
	v_cvt_pk_bf16_f32 v242, v80, v81
	v_cvt_pk_bf16_f32 v243, v82, v83
	v_mul_f32_e32 v81, v81, v81
	v_mul_f32_e32 v83, v83, v83
	v_fmac_f32_e32 v81, v80, v80
	v_fmac_f32_e32 v83, v82, v82
	v_add_f32_e32 v80, v81, v83
	v_add_f32_e32 v80, v86, v80
	v_mov_b32_e32 v81, v80
	s_nop 1
	v_permlane16_swap_b32 v80, v81
	global_store_dwordx4 v[102:103], v[240:243], off offset:-8
	v_add_f32_e32 v80, v80, v81
	v_mov_b32_e32 v81, v80
	s_nop 1
	v_permlane32_swap_b32 v80, v81
	s_and_saveexec_b64 s[12:13], s[2:3]
	s_cbranch_execz .LBB0_1214
	v_lshl_add_u64 v[82:83], v[96:97], 2, s[8:9]
	v_add_f32_e32 v80, v80, v81
	global_atomic_add_f32 v[82:83], v80, off
; __device__ __forceinline__ unsigned pk2(float lo, float hi) { f32x2_t v = {lo, hi}; bf16x2_t b = __builtin_convertvector(v, bf16x2_t); return __builtin_bit_cast(unsigned, b); }
; __device__ __forceinline__ float xor16_sum(float v) { float a = v, b = v; swap16(a, b); return a + b; }
; __device__ __forceinline__ float xor32_sum(float v) { float a = v, b = v; swap32(a, b); return a + b; }
;     __device__ __forceinline__ void operator()(const f32x4 (&acc)[2][2][4][2], const Unit& u, int wr, int wc, int fr, int fq) const {
;     ...
;         for (int ai = 0; ai < 2; ++ai)
; #pragma unroll
;             for (int m = 0; m < 4; ++m) {
;                 const int row = row0 + ai * HALF + m * 16; float sq = 0.f;
; #pragma unroll
;                 for (int bj = 0; bj < 2; ++bj)
; #pragma unroll
;                     for (int n = 0; n < 2; ++n) {
;                         const size_t idx = (size_t)row * ldc + u.pn * BM + bj * HALF + wc * 32 + 8 * fq + 4 * n;
;                         const f32x4 b = *(const f32x4*)(base + idx);
;                         const f32x4 v = b + acc[ai][bj][m][n] * alpha;
;                         *(f32x4*)(out + idx) = v;
;                         if (NORM) { u32x2 w; w.x = pk2(v[0], v[1]); w.y = pk2(v[2], v[3]); *(u32x2*)(xb + idx) = w; sq += (v[0] * v[0] + v[1] * v[1]) + (v[2] * v[2] + v[3] * v[3]); }
;                     }
;                 if (NORM) { sq = xor16_sum(sq); sq = xor32_sum(sq); if (fq == 0) __hip_atomic_fetch_add(ss + row, sq, __ATOMIC_RELAXED, __HIP_MEMORY_SCOPE_AGENT); }
.LBB0_1214:
	s_or_b64 exec, exec, s[12:13]
	v_or_b32_e32 v80, 48, v148
	v_ashrrev_i32_e32 v81, 31, v80
	v_lshlrev_b64 v[82:83], 11, v[80:81]
	v_lshl_add_u64 v[86:87], v[82:83], 0, v[146:147]
	v_lshl_add_u64 v[88:89], v[86:87], 2, s[30:31]
	s_nop 0
	v_lshlrev_b64 v[86:87], 1, v[86:87]
	v_lshl_add_u64 v[90:91], s[6:7], 0, v[86:87]
	s_nop 0
	s_waitcnt vmcnt(30)
	v_pk_add_f32 v[78:79], v[78:79], v[218:219]
	v_pk_add_f32 v[76:77], v[76:77], v[216:217]
	v_cvt_pk_bf16_f32 v241, v78, v79
	v_cvt_pk_bf16_f32 v240, v76, v77
	global_store_dwordx4 v[88:89], v[76:79], off
	s_nop 0
	s_nop 0
	v_or_b32_e32 v90, 8, v86
	v_mov_b32_e32 v91, v87
	v_lshl_add_u64 v[90:91], s[6:7], 0, v[90:91]
	v_mul_f32_e32 v77, v77, v77
	v_mul_f32_e32 v79, v79, v79
	v_fmac_f32_e32 v77, v76, v76
	v_fmac_f32_e32 v79, v78, v78
	v_add_f32_e32 v76, v77, v79
	s_nop 0
	v_pk_add_f32 v[74:75], v[74:75], v[222:223]
	v_pk_add_f32 v[72:73], v[72:73], v[220:221]
	v_cvt_pk_bf16_f32 v243, v74, v75
	v_cvt_pk_bf16_f32 v242, v72, v73
	global_store_dwordx4 v[88:89], v[72:75], off offset:16
	global_store_dwordx4 v[90:91], v[240:243], off offset:-8
	s_nop 0
	v_or_b32_e32 v90, 0x100, v86
	v_mov_b32_e32 v91, v87
	v_lshl_add_u64 v[90:91], s[6:7], 0, v[90:91]
	v_mul_f32_e32 v73, v73, v73
	v_mul_f32_e32 v75, v75, v75
	v_fmac_f32_e32 v73, v72, v72
	v_fmac_f32_e32 v75, v74, v74
	v_add_f32_e32 v72, v73, v75
	v_add_f32_e32 v72, v76, v72
	v_or_b32_e32 v86, 0x108, v86
	v_lshl_add_u64 v[86:87], s[6:7], 0, v[86:87]
	s_nop 0
	v_pk_add_f32 v[70:71], v[70:71], v[226:227]
	v_pk_add_f32 v[68:69], v[68:69], v[224:225]
	v_cvt_pk_bf16_f32 v241, v70, v71
	v_cvt_pk_bf16_f32 v240, v68, v69
	global_store_dwordx4 v[88:89], v[68:71], off offset:512
	s_nop 0
	s_nop 0
	v_mul_f32_e32 v69, v69, v69
	v_mul_f32_e32 v71, v71, v71
	v_fmac_f32_e32 v69, v68, v68
	v_fmac_f32_e32 v71, v70, v70
	v_add_f32_e32 v68, v69, v71
	v_add_f32_e32 v70, v72, v68
	s_nop 0
	v_pk_add_f32 v[66:67], v[66:67], v[236:237]
	v_pk_add_f32 v[64:65], v[64:65], v[234:235]
	v_mov_b32_e32 v230, 0x160000
	v_lshl_add_u64 v[228:229], v[232:233], 0, v[230:231]
	global_load_dwordx4 v[216:219], v[228:229], off nt
	global_load_dwordx4 v[220:223], v[228:229], off offset:16 nt
	global_load_dwordx4 v[224:227], v[228:229], off offset:512 nt
	global_load_dwordx4 v[234:237], v[228:229], off offset:528 nt
	global_store_dwordx4 v[88:89], v[64:67], off offset:528
	v_cvt_pk_bf16_f32 v242, v64, v65
	v_cvt_pk_bf16_f32 v243, v66, v67
	v_mul_f32_e32 v65, v65, v65
	v_mul_f32_e32 v67, v67, v67
	v_fmac_f32_e32 v65, v64, v64
	v_fmac_f32_e32 v67, v66, v66
	v_add_f32_e32 v64, v65, v67
	v_add_f32_e32 v64, v70, v64
	v_mov_b32_e32 v65, v64
	s_nop 1
	v_permlane16_swap_b32 v64, v65
	global_store_dwordx4 v[86:87], v[240:243], off offset:-8
	v_add_f32_e32 v64, v64, v65
	v_mov_b32_e32 v65, v64
	s_nop 1
	v_permlane32_swap_b32 v64, v65
	s_and_saveexec_b64 s[12:13], s[2:3]
	s_cbranch_execz .LBB0_1216
	v_lshl_add_u64 v[66:67], v[80:81], 2, s[8:9]
	v_add_f32_e32 v64, v64, v65
	global_atomic_add_f32 v[66:67], v64, off
.LBB0_1216:
	s_or_b64 exec, exec, s[12:13]
	v_add_u32_e32 v64, 0x80, v148
	v_ashrrev_i32_e32 v65, 31, v64
	v_lshlrev_b64 v[66:67], 11, v[64:65]
	v_lshl_add_u64 v[70:71], v[66:67], 0, v[146:147]
	v_lshl_add_u64 v[72:73], v[70:71], 2, s[30:31]
	s_nop 0
	v_lshlrev_b64 v[70:71], 1, v[70:71]
	v_lshl_add_u64 v[74:75], s[6:7], 0, v[70:71]
	s_nop 0
	s_waitcnt vmcnt(32)
	v_pk_add_f32 v[62:63], v[62:63], v[166:167]
	v_pk_add_f32 v[60:61], v[60:61], v[164:165]
	v_cvt_pk_bf16_f32 v241, v62, v63
	v_cvt_pk_bf16_f32 v240, v60, v61
	global_store_dwordx4 v[72:73], v[60:63], off
	s_nop 0
	s_nop 0
	v_or_b32_e32 v74, 8, v70
	v_mov_b32_e32 v75, v71
	v_lshl_add_u64 v[74:75], s[6:7], 0, v[74:75]
	v_mul_f32_e32 v61, v61, v61
	v_mul_f32_e32 v63, v63, v63
	v_fmac_f32_e32 v61, v60, v60
	v_fmac_f32_e32 v63, v62, v62
	v_add_f32_e32 v60, v61, v63
	s_nop 0
	v_pk_add_f32 v[58:59], v[58:59], v[170:171]
	v_pk_add_f32 v[56:57], v[56:57], v[168:169]
	v_cvt_pk_bf16_f32 v243, v58, v59
	v_cvt_pk_bf16_f32 v242, v56, v57
	global_store_dwordx4 v[72:73], v[56:59], off offset:16
	global_store_dwordx4 v[74:75], v[240:243], off offset:-8
	s_nop 0
	v_or_b32_e32 v74, 0x100, v70
	v_mov_b32_e32 v75, v71
	v_lshl_add_u64 v[74:75], s[6:7], 0, v[74:75]
	v_mul_f32_e32 v57, v57, v57
	v_mul_f32_e32 v59, v59, v59
	v_fmac_f32_e32 v57, v56, v56
	v_fmac_f32_e32 v59, v58, v58
	v_add_f32_e32 v56, v57, v59
	v_add_f32_e32 v56, v60, v56
	v_or_b32_e32 v70, 0x108, v70
	v_lshl_add_u64 v[70:71], s[6:7], 0, v[70:71]
	s_nop 0
	v_pk_add_f32 v[54:55], v[54:55], v[174:175]
	v_pk_add_f32 v[52:53], v[52:53], v[172:173]
	v_cvt_pk_bf16_f32 v241, v54, v55
	v_cvt_pk_bf16_f32 v240, v52, v53
	global_store_dwordx4 v[72:73], v[52:55], off offset:512
	s_nop 0
	s_nop 0
	v_mul_f32_e32 v53, v53, v53
	v_mul_f32_e32 v55, v55, v55
	v_fmac_f32_e32 v53, v52, v52
	v_fmac_f32_e32 v55, v54, v54
	v_add_f32_e32 v52, v53, v55
	v_add_f32_e32 v54, v56, v52
	s_nop 0
	v_pk_add_f32 v[50:51], v[50:51], v[178:179]
	v_pk_add_f32 v[48:49], v[48:49], v[176:177]
	global_store_dwordx4 v[72:73], v[48:51], off offset:528
	v_cvt_pk_bf16_f32 v242, v48, v49
	v_cvt_pk_bf16_f32 v243, v50, v51
	v_mul_f32_e32 v49, v49, v49
	v_mul_f32_e32 v51, v51, v51
	v_fmac_f32_e32 v49, v48, v48
	v_fmac_f32_e32 v51, v50, v50
	v_add_f32_e32 v48, v49, v51
	v_add_f32_e32 v48, v54, v48
	v_mov_b32_e32 v49, v48
	s_nop 1
	v_permlane16_swap_b32 v48, v49
	global_store_dwordx4 v[70:71], v[240:243], off offset:-8
	v_add_f32_e32 v48, v48, v49
	v_mov_b32_e32 v49, v48
	s_nop 1
	v_permlane32_swap_b32 v48, v49
	s_and_saveexec_b64 s[12:13], s[2:3]
	s_cbranch_execz .LBB0_1218
	v_lshl_add_u64 v[50:51], v[64:65], 2, s[8:9]
	v_add_f32_e32 v48, v48, v49
	global_atomic_add_f32 v[50:51], v48, off
; __device__ __forceinline__ unsigned pk2(float lo, float hi) { f32x2_t v = {lo, hi}; bf16x2_t b = __builtin_convertvector(v, bf16x2_t); return __builtin_bit_cast(unsigned, b); }
; __device__ __forceinline__ float xor16_sum(float v) { float a = v, b = v; swap16(a, b); return a + b; }
; __device__ __forceinline__ float xor32_sum(float v) { float a = v, b = v; swap32(a, b); return a + b; }
;     __device__ __forceinline__ void operator()(const f32x4 (&acc)[2][2][4][2], const Unit& u, int wr, int wc, int fr, int fq) const {
;     ...
;         for (int ai = 0; ai < 2; ++ai)
; #pragma unroll
;             for (int m = 0; m < 4; ++m) {
;                 const int row = row0 + ai * HALF + m * 16; float sq = 0.f;
; #pragma unroll
;                 for (int bj = 0; bj < 2; ++bj)
; #pragma unroll
;                     for (int n = 0; n < 2; ++n) {
;                         const size_t idx = (size_t)row * ldc + u.pn * BM + bj * HALF + wc * 32 + 8 * fq + 4 * n;
;                         const f32x4 b = *(const f32x4*)(base + idx);
;                         const f32x4 v = b + acc[ai][bj][m][n] * alpha;
;                         *(f32x4*)(out + idx) = v;
;                         if (NORM) { u32x2 w; w.x = pk2(v[0], v[1]); w.y = pk2(v[2], v[3]); *(u32x2*)(xb + idx) = w; sq += (v[0] * v[0] + v[1] * v[1]) + (v[2] * v[2] + v[3] * v[3]); }
;                     }
;                 if (NORM) { sq = xor16_sum(sq); sq = xor32_sum(sq); if (fq == 0) __hip_atomic_fetch_add(ss + row, sq, __ATOMIC_RELAXED, __HIP_MEMORY_SCOPE_AGENT); }
.LBB0_1218:
	s_or_b64 exec, exec, s[12:13]
	v_add_u32_e32 v48, 0x90, v148
	v_ashrrev_i32_e32 v49, 31, v48
	v_lshlrev_b64 v[50:51], 11, v[48:49]
	v_lshl_add_u64 v[54:55], v[50:51], 0, v[146:147]
	v_lshl_add_u64 v[56:57], v[54:55], 2, s[30:31]
	s_nop 0
	v_lshlrev_b64 v[54:55], 1, v[54:55]
	v_lshl_add_u64 v[58:59], s[6:7], 0, v[54:55]
	s_nop 0
	s_waitcnt vmcnt(28)
	v_pk_add_f32 v[46:47], v[46:47], v[182:183]
	v_pk_add_f32 v[44:45], v[44:45], v[180:181]
	v_cvt_pk_bf16_f32 v241, v46, v47
	v_cvt_pk_bf16_f32 v240, v44, v45
	global_store_dwordx4 v[56:57], v[44:47], off
	s_nop 0
	s_nop 0
	v_or_b32_e32 v58, 8, v54
	v_mov_b32_e32 v59, v55
	v_lshl_add_u64 v[58:59], s[6:7], 0, v[58:59]
	v_mul_f32_e32 v45, v45, v45
	v_mul_f32_e32 v47, v47, v47
	v_fmac_f32_e32 v45, v44, v44
	v_fmac_f32_e32 v47, v46, v46
	v_add_f32_e32 v44, v45, v47
	s_nop 0
	v_pk_add_f32 v[42:43], v[42:43], v[190:191]
	v_pk_add_f32 v[40:41], v[40:41], v[188:189]
	v_cvt_pk_bf16_f32 v243, v42, v43
	v_cvt_pk_bf16_f32 v242, v40, v41
	global_store_dwordx4 v[56:57], v[40:43], off offset:16
	global_store_dwordx4 v[58:59], v[240:243], off offset:-8
	s_nop 0
	v_or_b32_e32 v58, 0x100, v54
	v_mov_b32_e32 v59, v55
	v_lshl_add_u64 v[58:59], s[6:7], 0, v[58:59]
	v_mul_f32_e32 v41, v41, v41
	v_mul_f32_e32 v43, v43, v43
	v_fmac_f32_e32 v41, v40, v40
	v_fmac_f32_e32 v43, v42, v42
	v_add_f32_e32 v40, v41, v43
	v_add_f32_e32 v40, v44, v40
	v_or_b32_e32 v54, 0x108, v54
	v_lshl_add_u64 v[54:55], s[6:7], 0, v[54:55]
	s_nop 0
	v_pk_add_f32 v[38:39], v[38:39], v[194:195]
	v_pk_add_f32 v[36:37], v[36:37], v[192:193]
	v_cvt_pk_bf16_f32 v241, v38, v39
	v_cvt_pk_bf16_f32 v240, v36, v37
	global_store_dwordx4 v[56:57], v[36:39], off offset:512
	s_nop 0
	s_nop 0
	v_mul_f32_e32 v37, v37, v37
	v_mul_f32_e32 v39, v39, v39
	v_fmac_f32_e32 v37, v36, v36
	v_fmac_f32_e32 v39, v38, v38
	v_add_f32_e32 v36, v37, v39
	v_add_f32_e32 v38, v40, v36
	s_nop 0
	v_pk_add_f32 v[34:35], v[34:35], v[198:199]
	v_pk_add_f32 v[32:33], v[32:33], v[196:197]
	global_store_dwordx4 v[56:57], v[32:35], off offset:528
	v_cvt_pk_bf16_f32 v242, v32, v33
	v_cvt_pk_bf16_f32 v243, v34, v35
	v_mul_f32_e32 v33, v33, v33
	v_mul_f32_e32 v35, v35, v35
	v_fmac_f32_e32 v33, v32, v32
	v_fmac_f32_e32 v35, v34, v34
	v_add_f32_e32 v32, v33, v35
	v_add_f32_e32 v32, v38, v32
	v_mov_b32_e32 v33, v32
	s_nop 1
	v_permlane16_swap_b32 v32, v33
	global_store_dwordx4 v[54:55], v[240:243], off offset:-8
	v_add_f32_e32 v32, v32, v33
	v_mov_b32_e32 v33, v32
	s_nop 1
	v_permlane32_swap_b32 v32, v33
	s_and_saveexec_b64 s[12:13], s[2:3]
	s_cbranch_execz .LBB0_1220
	v_lshl_add_u64 v[34:35], v[48:49], 2, s[8:9]
	v_add_f32_e32 v32, v32, v33
	global_atomic_add_f32 v[34:35], v32, off
; __device__ __forceinline__ unsigned pk2(float lo, float hi) { f32x2_t v = {lo, hi}; bf16x2_t b = __builtin_convertvector(v, bf16x2_t); return __builtin_bit_cast(unsigned, b); }
; __device__ __forceinline__ float xor16_sum(float v) { float a = v, b = v; swap16(a, b); return a + b; }
; __device__ __forceinline__ float xor32_sum(float v) { float a = v, b = v; swap32(a, b); return a + b; }
;     __device__ __forceinline__ void operator()(const f32x4 (&acc)[2][2][4][2], const Unit& u, int wr, int wc, int fr, int fq) const {
;     ...
;         for (int ai = 0; ai < 2; ++ai)
; #pragma unroll
;             for (int m = 0; m < 4; ++m) {
;                 const int row = row0 + ai * HALF + m * 16; float sq = 0.f;
; #pragma unroll
;                 for (int bj = 0; bj < 2; ++bj)
; #pragma unroll
;                     for (int n = 0; n < 2; ++n) {
;                         const size_t idx = (size_t)row * ldc + u.pn * BM + bj * HALF + wc * 32 + 8 * fq + 4 * n;
;                         const f32x4 b = *(const f32x4*)(base + idx);
;                         const f32x4 v = b + acc[ai][bj][m][n] * alpha;
;                         *(f32x4*)(out + idx) = v;
;                         if (NORM) { u32x2 w; w.x = pk2(v[0], v[1]); w.y = pk2(v[2], v[3]); *(u32x2*)(xb + idx) = w; sq += (v[0] * v[0] + v[1] * v[1]) + (v[2] * v[2] + v[3] * v[3]); }
;                     }
;                 if (NORM) { sq = xor16_sum(sq); sq = xor32_sum(sq); if (fq == 0) __hip_atomic_fetch_add(ss + row, sq, __ATOMIC_RELAXED, __HIP_MEMORY_SCOPE_AGENT); }
.LBB0_1220:
	s_or_b64 exec, exec, s[12:13]
	v_add_u32_e32 v32, 0xa0, v148
	v_ashrrev_i32_e32 v33, 31, v32
	v_lshlrev_b64 v[34:35], 11, v[32:33]
	v_lshl_add_u64 v[38:39], v[34:35], 0, v[146:147]
	v_lshl_add_u64 v[40:41], v[38:39], 2, s[30:31]
	s_nop 0
	v_lshlrev_b64 v[38:39], 1, v[38:39]
	v_lshl_add_u64 v[42:43], s[6:7], 0, v[38:39]
	s_nop 0
	s_waitcnt vmcnt(24)
	v_pk_add_f32 v[30:31], v[30:31], v[202:203]
	v_pk_add_f32 v[28:29], v[28:29], v[200:201]
	v_cvt_pk_bf16_f32 v241, v30, v31
	v_cvt_pk_bf16_f32 v240, v28, v29
	global_store_dwordx4 v[40:41], v[28:31], off
	s_nop 0
	s_nop 0
	v_or_b32_e32 v42, 8, v38
	v_mov_b32_e32 v43, v39
	v_lshl_add_u64 v[42:43], s[6:7], 0, v[42:43]
	v_mul_f32_e32 v29, v29, v29
	v_mul_f32_e32 v31, v31, v31
	v_fmac_f32_e32 v29, v28, v28
	v_fmac_f32_e32 v31, v30, v30
	v_add_f32_e32 v28, v29, v31
	s_nop 0
	v_pk_add_f32 v[26:27], v[26:27], v[206:207]
	v_pk_add_f32 v[24:25], v[24:25], v[204:205]
	v_cvt_pk_bf16_f32 v243, v26, v27
	v_cvt_pk_bf16_f32 v242, v24, v25
	global_store_dwordx4 v[40:41], v[24:27], off offset:16
	global_store_dwordx4 v[42:43], v[240:243], off offset:-8
	s_nop 0
	v_or_b32_e32 v42, 0x100, v38
	v_mov_b32_e32 v43, v39
	v_lshl_add_u64 v[42:43], s[6:7], 0, v[42:43]
	v_mul_f32_e32 v25, v25, v25
	v_mul_f32_e32 v27, v27, v27
	v_fmac_f32_e32 v25, v24, v24
	v_fmac_f32_e32 v27, v26, v26
	v_add_f32_e32 v24, v25, v27
	v_add_f32_e32 v24, v28, v24
	v_or_b32_e32 v38, 0x108, v38
	v_lshl_add_u64 v[38:39], s[6:7], 0, v[38:39]
	s_nop 0
	v_pk_add_f32 v[22:23], v[22:23], v[210:211]
	v_pk_add_f32 v[20:21], v[20:21], v[208:209]
	v_cvt_pk_bf16_f32 v241, v22, v23
	v_cvt_pk_bf16_f32 v240, v20, v21
	global_store_dwordx4 v[40:41], v[20:23], off offset:512
	s_nop 0
	s_nop 0
	v_mul_f32_e32 v21, v21, v21
	v_mul_f32_e32 v23, v23, v23
	v_fmac_f32_e32 v21, v20, v20
	v_fmac_f32_e32 v23, v22, v22
	v_add_f32_e32 v20, v21, v23
	v_add_f32_e32 v22, v24, v20
	s_nop 0
	v_pk_add_f32 v[18:19], v[18:19], v[214:215]
	v_pk_add_f32 v[16:17], v[16:17], v[212:213]
	global_store_dwordx4 v[40:41], v[16:19], off offset:528
	v_cvt_pk_bf16_f32 v242, v16, v17
	v_cvt_pk_bf16_f32 v243, v18, v19
	v_mul_f32_e32 v17, v17, v17
	v_mul_f32_e32 v19, v19, v19
	v_fmac_f32_e32 v17, v16, v16
	v_fmac_f32_e32 v19, v18, v18
	v_add_f32_e32 v16, v17, v19
	v_add_f32_e32 v16, v22, v16
	v_mov_b32_e32 v17, v16
	s_nop 1
	v_permlane16_swap_b32 v16, v17
	global_store_dwordx4 v[38:39], v[240:243], off offset:-8
	v_add_f32_e32 v16, v16, v17
	v_mov_b32_e32 v17, v16
	s_nop 1
	v_permlane32_swap_b32 v16, v17
	s_and_saveexec_b64 s[12:13], s[2:3]
	s_cbranch_execz .LBB0_1222
	v_lshl_add_u64 v[18:19], v[32:33], 2, s[8:9]
	v_add_f32_e32 v16, v16, v17
	global_atomic_add_f32 v[18:19], v16, off
.LBB0_1222:
	s_or_b64 exec, exec, s[12:13]
	v_add_u32_e32 v16, 0xb0, v148
	v_ashrrev_i32_e32 v17, 31, v16
	v_lshlrev_b64 v[18:19], 11, v[16:17]
	v_lshl_add_u64 v[22:23], v[18:19], 0, v[146:147]
	v_lshl_add_u64 v[24:25], v[22:23], 2, s[30:31]
	s_nop 0
	v_lshlrev_b64 v[22:23], 1, v[22:23]
	v_lshl_add_u64 v[26:27], s[6:7], 0, v[22:23]
	s_nop 0
	s_waitcnt vmcnt(20)
	v_pk_add_f32 v[14:15], v[14:15], v[218:219]
	v_pk_add_f32 v[12:13], v[12:13], v[216:217]
	v_cvt_pk_bf16_f32 v241, v14, v15
	v_cvt_pk_bf16_f32 v240, v12, v13
	global_store_dwordx4 v[24:25], v[12:15], off
	s_nop 0
	s_nop 0
	v_or_b32_e32 v26, 8, v22
	v_mov_b32_e32 v27, v23
	v_lshl_add_u64 v[26:27], s[6:7], 0, v[26:27]
	v_mul_f32_e32 v13, v13, v13
	v_mul_f32_e32 v15, v15, v15
	v_fmac_f32_e32 v13, v12, v12
	v_fmac_f32_e32 v15, v14, v14
	v_add_f32_e32 v12, v13, v15
	s_nop 0
	v_pk_add_f32 v[10:11], v[10:11], v[222:223]
	v_pk_add_f32 v[8:9], v[8:9], v[220:221]
	v_cvt_pk_bf16_f32 v243, v10, v11
	v_cvt_pk_bf16_f32 v242, v8, v9
	global_store_dwordx4 v[24:25], v[8:11], off offset:16
	global_store_dwordx4 v[26:27], v[240:243], off offset:-8
	s_nop 0
	v_or_b32_e32 v26, 0x100, v22
	v_mov_b32_e32 v27, v23
	v_lshl_add_u64 v[26:27], s[6:7], 0, v[26:27]
	v_mul_f32_e32 v9, v9, v9
	v_mul_f32_e32 v11, v11, v11
	v_fmac_f32_e32 v9, v8, v8
	v_fmac_f32_e32 v11, v10, v10
	v_add_f32_e32 v8, v9, v11
	v_add_f32_e32 v8, v12, v8
	v_or_b32_e32 v22, 0x108, v22
	v_lshl_add_u64 v[22:23], s[6:7], 0, v[22:23]
	s_nop 0
	v_pk_add_f32 v[6:7], v[6:7], v[226:227]
	v_pk_add_f32 v[4:5], v[4:5], v[224:225]
	v_cvt_pk_bf16_f32 v241, v6, v7
	v_cvt_pk_bf16_f32 v240, v4, v5
	global_store_dwordx4 v[24:25], v[4:7], off offset:512
	s_nop 0
	s_nop 0
	v_mul_f32_e32 v5, v5, v5
	v_mul_f32_e32 v7, v7, v7
	v_fmac_f32_e32 v5, v4, v4
	v_fmac_f32_e32 v7, v6, v6
	v_add_f32_e32 v4, v5, v7
	v_add_f32_e32 v6, v8, v4
	s_nop 0
	v_pk_add_f32 v[2:3], v[2:3], v[236:237]
	v_pk_add_f32 v[0:1], v[0:1], v[234:235]
	global_store_dwordx4 v[24:25], v[0:3], off offset:528
	v_cvt_pk_bf16_f32 v242, v0, v1
	v_cvt_pk_bf16_f32 v243, v2, v3
	v_mul_f32_e32 v1, v1, v1
	v_mul_f32_e32 v3, v3, v3
	v_fmac_f32_e32 v1, v0, v0
	v_fmac_f32_e32 v3, v2, v2
	v_add_f32_e32 v0, v1, v3
	v_add_f32_e32 v0, v6, v0
	v_mov_b32_e32 v1, v0
	s_nop 1
	v_permlane16_swap_b32 v0, v1
	global_store_dwordx4 v[22:23], v[240:243], off offset:-8
	v_add_f32_e32 v0, v0, v1
	v_mov_b32_e32 v1, v0
	s_nop 1
	v_permlane32_swap_b32 v0, v1
	s_and_saveexec_b64 s[12:13], s[2:3]
	s_cbranch_execz .LBB0_1224
	v_lshl_add_u64 v[2:3], v[16:17], 2, s[8:9]
	v_add_f32_e32 v0, v0, v1
	global_atomic_add_f32 v[2:3], v0, off

; __device__ __forceinline__ unsigned pk2(float lo, float hi) { f32x2_t v = {lo, hi}; bf16x2_t b = __builtin_convertvector(v, bf16x2_t); return __builtin_bit_cast(unsigned, b); }
; __device__ __forceinline__ float xor16_sum(float v) { float a = v, b = v; swap16(a, b); return a + b; }
; __device__ __forceinline__ float xor32_sum(float v) { float a = v, b = v; swap32(a, b); return a + b; }
;     __device__ __forceinline__ void operator()(const f32x4 (&acc)[2][2][4][2], const Unit& u, int wr, int wc, int fr, int fq) const {
;         const int row0 = u.pm * BM + wr * 64 + fr; constexpr int ldc = 2048; constexpr float alpha = 0.5f * ALPHA2;
;         bf16_t* const xb = (bf16_t*)(ws + XBOFF); __attribute__((address_space(1))) float* const ss = (__attribute__((address_space(1))) float*)(ws + SSOFF);
; #pragma unroll
;         for (int ai = 0; ai < 2; ++ai)
; #pragma unroll
;             for (int m = 0; m < 4; ++m) {
;                 const int row = row0 + ai * HALF + m * 16; float sq = 0.f;
; #pragma unroll
;                 for (int bj = 0; bj < 2; ++bj)
; #pragma unroll
;                     for (int n = 0; n < 2; ++n) {
;                         const size_t idx = (size_t)row * ldc + u.pn * BM + bj * HALF + wc * 32 + 8 * fq + 4 * n;
;                         const f32x4 b = *(const f32x4*)(base + idx);
;                         const f32x4 v = b + acc[ai][bj][m][n] * alpha;
;                         *(f32x4*)(out + idx) = v;
;                         if (NORM) { u32x2 w; w.x = pk2(v[0], v[1]); w.y = pk2(v[2], v[3]); *(u32x2*)(xb + idx) = w; sq += (v[0] * v[0] + v[1] * v[1]) + (v[2] * v[2] + v[3] * v[3]); }
;                     }
;                 if (NORM) { sq = xor16_sum(sq); sq = xor32_sum(sq); if (fq == 0) __hip_atomic_fetch_add(ss + row, sq, __ATOMIC_RELAXED, __HIP_MEMORY_SCOPE_AGENT); }
.LBB0_1605:
	v_lshl_add_u32 v148, s12, 8, v137
	s_lshl_b32 s12, s28, 8
	s_ashr_i32 s13, s12, 31
	v_ashrrev_i32_e32 v149, 31, v148
	v_mov_b32_e32 v147, s13
	v_or_b32_e32 v146, s12, v136
	v_lshlrev_b64 v[154:155], 11, v[148:149]
	v_lshl_add_u64 v[158:159], v[154:155], 0, v[146:147]
	v_lshl_add_u64 v[160:161], v[158:159], 2, s[30:31]
	v_mov_b32_e32 v232, v160
	v_mov_b32_e32 v233, v161
	v_mov_b32_e32 v231, 0
	v_mov_b32_e32 v230, 0x0
	v_lshl_add_u64 v[228:229], v[232:233], 0, v[230:231]
	global_load_dwordx4 v[164:167], v[228:229], off nt
	global_load_dwordx4 v[168:171], v[228:229], off offset:16 nt
	global_load_dwordx4 v[172:175], v[228:229], off offset:512 nt
	global_load_dwordx4 v[176:179], v[228:229], off offset:528 nt
	v_mov_b32_e32 v230, 0x20000
	v_lshl_add_u64 v[228:229], v[232:233], 0, v[230:231]
	global_load_dwordx4 v[180:183], v[228:229], off nt
	global_load_dwordx4 v[188:191], v[228:229], off offset:16 nt
	global_load_dwordx4 v[192:195], v[228:229], off offset:512 nt
	global_load_dwordx4 v[196:199], v[228:229], off offset:528 nt
	v_mov_b32_e32 v230, 0x40000
	v_lshl_add_u64 v[228:229], v[232:233], 0, v[230:231]
	global_load_dwordx4 v[200:203], v[228:229], off nt
	global_load_dwordx4 v[204:207], v[228:229], off offset:16 nt
	global_load_dwordx4 v[208:211], v[228:229], off offset:512 nt
	global_load_dwordx4 v[212:215], v[228:229], off offset:528 nt
	v_mov_b32_e32 v230, 0x60000
	v_lshl_add_u64 v[228:229], v[232:233], 0, v[230:231]
	global_load_dwordx4 v[216:219], v[228:229], off nt
	global_load_dwordx4 v[220:223], v[228:229], off offset:16 nt
	global_load_dwordx4 v[224:227], v[228:229], off offset:512 nt
	global_load_dwordx4 v[234:237], v[228:229], off offset:528 nt
	s_nop 0
	v_lshlrev_b64 v[158:159], 1, v[158:159]
	v_lshl_add_u64 v[162:163], s[40:41], 0, v[158:159]
	s_nop 0
	s_waitcnt vmcnt(12)
	v_pk_add_f32 v[126:127], v[126:127], v[166:167]
	v_pk_add_f32 v[124:125], v[124:125], v[164:165]
	v_cvt_pk_bf16_f32 v241, v126, v127
	v_cvt_pk_bf16_f32 v240, v124, v125
	global_store_dwordx4 v[160:161], v[124:127], off
	s_nop 0
	s_nop 0
	v_or_b32_e32 v162, 8, v158
	v_mov_b32_e32 v163, v159
	v_lshl_add_u64 v[162:163], s[40:41], 0, v[162:163]
	v_mul_f32_e32 v125, v125, v125
	v_mul_f32_e32 v127, v127, v127
	v_fmac_f32_e32 v125, v124, v124
	v_fmac_f32_e32 v127, v126, v126
	v_add_f32_e32 v124, v125, v127
	s_nop 0
	v_pk_add_f32 v[122:123], v[122:123], v[170:171]
	v_pk_add_f32 v[120:121], v[120:121], v[168:169]
	v_cvt_pk_bf16_f32 v243, v122, v123
	v_cvt_pk_bf16_f32 v242, v120, v121
	global_store_dwordx4 v[160:161], v[120:123], off offset:16
	global_store_dwordx4 v[162:163], v[240:243], off offset:-8
	s_nop 0
	v_or_b32_e32 v162, 0x100, v158
	v_mov_b32_e32 v163, v159
	v_lshl_add_u64 v[162:163], s[40:41], 0, v[162:163]
	v_mul_f32_e32 v121, v121, v121
	v_mul_f32_e32 v123, v123, v123
	v_fmac_f32_e32 v121, v120, v120
	v_fmac_f32_e32 v123, v122, v122
	v_add_f32_e32 v120, v121, v123
	v_add_f32_e32 v120, v124, v120
	v_or_b32_e32 v158, 0x108, v158
	v_lshl_add_u64 v[158:159], s[40:41], 0, v[158:159]
	s_nop 0
	v_pk_add_f32 v[118:119], v[118:119], v[174:175]
	v_pk_add_f32 v[116:117], v[116:117], v[172:173]
	v_cvt_pk_bf16_f32 v241, v118, v119
	v_cvt_pk_bf16_f32 v240, v116, v117
	global_store_dwordx4 v[160:161], v[116:119], off offset:512
	s_nop 0
	s_nop 0
	v_mul_f32_e32 v117, v117, v117
	v_mul_f32_e32 v119, v119, v119
	v_fmac_f32_e32 v117, v116, v116
	v_fmac_f32_e32 v119, v118, v118
	v_add_f32_e32 v116, v117, v119
	v_add_f32_e32 v118, v120, v116
	s_nop 0
	v_pk_add_f32 v[114:115], v[114:115], v[178:179]
	v_pk_add_f32 v[112:113], v[112:113], v[176:177]
	v_mov_b32_e32 v230, 0x100000
	v_lshl_add_u64 v[228:229], v[232:233], 0, v[230:231]
	global_load_dwordx4 v[164:167], v[228:229], off nt
	global_load_dwordx4 v[168:171], v[228:229], off offset:16 nt
	global_load_dwordx4 v[172:175], v[228:229], off offset:512 nt
	global_load_dwordx4 v[176:179], v[228:229], off offset:528 nt
	global_store_dwordx4 v[160:161], v[112:115], off offset:528
	v_cvt_pk_bf16_f32 v242, v112, v113
	v_cvt_pk_bf16_f32 v243, v114, v115
	v_mul_f32_e32 v113, v113, v113
	v_mul_f32_e32 v115, v115, v115
	v_fmac_f32_e32 v113, v112, v112
	v_fmac_f32_e32 v115, v114, v114
	v_add_f32_e32 v112, v113, v115
	v_add_f32_e32 v112, v118, v112
	v_mov_b32_e32 v113, v112
	s_nop 1
	v_permlane16_swap_b32 v113, v112
	global_store_dwordx4 v[158:159], v[240:243], off offset:-8
	v_add_f32_e32 v112, v113, v112
	v_mov_b32_e32 v113, v112
	s_nop 1
	v_permlane32_swap_b32 v113, v112
	s_and_saveexec_b64 s[12:13], s[2:3]
	s_cbranch_execz .LBB0_1607
	v_lshl_add_u64 v[114:115], v[148:149], 2, s[6:7]
	v_add_f32_e32 v112, v113, v112
	global_atomic_add_f32 v[114:115], v112, off
; __device__ __forceinline__ unsigned pk2(float lo, float hi) { f32x2_t v = {lo, hi}; bf16x2_t b = __builtin_convertvector(v, bf16x2_t); return __builtin_bit_cast(unsigned, b); }
; __device__ __forceinline__ float xor16_sum(float v) { float a = v, b = v; swap16(a, b); return a + b; }
; __device__ __forceinline__ float xor32_sum(float v) { float a = v, b = v; swap32(a, b); return a + b; }
;     __device__ __forceinline__ void operator()(const f32x4 (&acc)[2][2][4][2], const Unit& u, int wr, int wc, int fr, int fq) const {
;     ...
;         for (int ai = 0; ai < 2; ++ai)
; #pragma unroll
;             for (int m = 0; m < 4; ++m) {
;                 const int row = row0 + ai * HALF + m * 16; float sq = 0.f;
; #pragma unroll
;                 for (int bj = 0; bj < 2; ++bj)
; #pragma unroll
;                     for (int n = 0; n < 2; ++n) {
;                         const size_t idx = (size_t)row * ldc + u.pn * BM + bj * HALF + wc * 32 + 8 * fq + 4 * n;
;                         const f32x4 b = *(const f32x4*)(base + idx);
;                         const f32x4 v = b + acc[ai][bj][m][n] * alpha;
;                         *(f32x4*)(out + idx) = v;
;                         if (NORM) { u32x2 w; w.x = pk2(v[0], v[1]); w.y = pk2(v[2], v[3]); *(u32x2*)(xb + idx) = w; sq += (v[0] * v[0] + v[1] * v[1]) + (v[2] * v[2] + v[3] * v[3]); }
;                     }
;                 if (NORM) { sq = xor16_sum(sq); sq = xor32_sum(sq); if (fq == 0) __hip_atomic_fetch_add(ss + row, sq, __ATOMIC_RELAXED, __HIP_MEMORY_SCOPE_AGENT); }
.LBB0_1607:
	s_or_b64 exec, exec, s[12:13]
	v_or_b32_e32 v112, 16, v148
	v_ashrrev_i32_e32 v113, 31, v112
	v_lshlrev_b64 v[114:115], 11, v[112:113]
	v_lshl_add_u64 v[118:119], v[114:115], 0, v[146:147]
	v_lshl_add_u64 v[120:121], v[118:119], 2, s[30:31]
	s_nop 0
	v_lshlrev_b64 v[118:119], 1, v[118:119]
	v_lshl_add_u64 v[122:123], s[40:41], 0, v[118:119]
	s_nop 0
	s_waitcnt vmcnt(18)
	v_pk_add_f32 v[110:111], v[110:111], v[182:183]
	v_pk_add_f32 v[108:109], v[108:109], v[180:181]
	v_cvt_pk_bf16_f32 v241, v110, v111
	v_cvt_pk_bf16_f32 v240, v108, v109
	global_store_dwordx4 v[120:121], v[108:111], off
	s_nop 0
	s_nop 0
	v_or_b32_e32 v122, 8, v118
	v_mov_b32_e32 v123, v119
	v_lshl_add_u64 v[122:123], s[40:41], 0, v[122:123]
	v_mul_f32_e32 v109, v109, v109
	v_mul_f32_e32 v111, v111, v111
	v_fmac_f32_e32 v109, v108, v108
	v_fmac_f32_e32 v111, v110, v110
	v_add_f32_e32 v108, v109, v111
	s_nop 0
	v_pk_add_f32 v[106:107], v[106:107], v[190:191]
	v_pk_add_f32 v[104:105], v[104:105], v[188:189]
	v_cvt_pk_bf16_f32 v243, v106, v107
	v_cvt_pk_bf16_f32 v242, v104, v105
	global_store_dwordx4 v[120:121], v[104:107], off offset:16
	global_store_dwordx4 v[122:123], v[240:243], off offset:-8
	s_nop 0
	v_or_b32_e32 v122, 0x100, v118
	v_mov_b32_e32 v123, v119
	v_lshl_add_u64 v[122:123], s[40:41], 0, v[122:123]
	v_mul_f32_e32 v105, v105, v105
	v_mul_f32_e32 v107, v107, v107
	v_fmac_f32_e32 v105, v104, v104
	v_fmac_f32_e32 v107, v106, v106
	v_add_f32_e32 v104, v105, v107
	v_add_f32_e32 v104, v108, v104
	v_or_b32_e32 v118, 0x108, v118
	v_lshl_add_u64 v[118:119], s[40:41], 0, v[118:119]
	s_nop 0
	v_pk_add_f32 v[102:103], v[102:103], v[194:195]
	v_pk_add_f32 v[100:101], v[100:101], v[192:193]
	v_cvt_pk_bf16_f32 v241, v102, v103
	v_cvt_pk_bf16_f32 v240, v100, v101
	global_store_dwordx4 v[120:121], v[100:103], off offset:512
	s_nop 0
	s_nop 0
	v_mul_f32_e32 v101, v101, v101
	v_mul_f32_e32 v103, v103, v103
	v_fmac_f32_e32 v101, v100, v100
	v_fmac_f32_e32 v103, v102, v102
	v_add_f32_e32 v100, v101, v103
	v_add_f32_e32 v102, v104, v100
	s_nop 0
	v_pk_add_f32 v[98:99], v[98:99], v[198:199]
	v_pk_add_f32 v[96:97], v[96:97], v[196:197]
	v_mov_b32_e32 v230, 0x120000
	v_lshl_add_u64 v[228:229], v[232:233], 0, v[230:231]
	global_load_dwordx4 v[180:183], v[228:229], off nt
	global_load_dwordx4 v[188:191], v[228:229], off offset:16 nt
	global_load_dwordx4 v[192:195], v[228:229], off offset:512 nt
	global_load_dwordx4 v[196:199], v[228:229], off offset:528 nt
	global_store_dwordx4 v[120:121], v[96:99], off offset:528
	v_cvt_pk_bf16_f32 v242, v96, v97
	v_cvt_pk_bf16_f32 v243, v98, v99
	v_mul_f32_e32 v97, v97, v97
	v_mul_f32_e32 v99, v99, v99
	v_fmac_f32_e32 v97, v96, v96
	v_fmac_f32_e32 v99, v98, v98
	v_add_f32_e32 v96, v97, v99
	v_add_f32_e32 v96, v102, v96
	v_mov_b32_e32 v97, v96
	s_nop 1
	v_permlane16_swap_b32 v96, v97
	global_store_dwordx4 v[118:119], v[240:243], off offset:-8
	v_add_f32_e32 v96, v96, v97
	v_mov_b32_e32 v97, v96
	s_nop 1
	v_permlane32_swap_b32 v96, v97
	s_and_saveexec_b64 s[12:13], s[2:3]
	s_cbranch_execz .LBB0_1609
	v_lshl_add_u64 v[98:99], v[112:113], 2, s[6:7]
	v_add_f32_e32 v96, v96, v97
	global_atomic_add_f32 v[98:99], v96, off
.LBB0_1609:
	s_or_b64 exec, exec, s[12:13]
	v_or_b32_e32 v96, 32, v148
	v_ashrrev_i32_e32 v97, 31, v96
	v_lshlrev_b64 v[98:99], 11, v[96:97]
	v_lshl_add_u64 v[102:103], v[98:99], 0, v[146:147]
	v_lshl_add_u64 v[104:105], v[102:103], 2, s[30:31]
	s_nop 0
	v_lshlrev_b64 v[102:103], 1, v[102:103]
	v_lshl_add_u64 v[106:107], s[40:41], 0, v[102:103]
	s_nop 0
	s_waitcnt vmcnt(24)
	v_pk_add_f32 v[94:95], v[94:95], v[202:203]
	v_pk_add_f32 v[92:93], v[92:93], v[200:201]
	v_cvt_pk_bf16_f32 v241, v94, v95
	v_cvt_pk_bf16_f32 v240, v92, v93
	global_store_dwordx4 v[104:105], v[92:95], off
	s_nop 0
	s_nop 0
	v_or_b32_e32 v106, 8, v102
	v_mov_b32_e32 v107, v103
	v_lshl_add_u64 v[106:107], s[40:41], 0, v[106:107]
	v_mul_f32_e32 v93, v93, v93
	v_mul_f32_e32 v95, v95, v95
	v_fmac_f32_e32 v93, v92, v92
	v_fmac_f32_e32 v95, v94, v94
	v_add_f32_e32 v92, v93, v95
	s_nop 0
	v_pk_add_f32 v[90:91], v[90:91], v[206:207]
	v_pk_add_f32 v[88:89], v[88:89], v[204:205]
	v_cvt_pk_bf16_f32 v243, v90, v91
	v_cvt_pk_bf16_f32 v242, v88, v89
	global_store_dwordx4 v[104:105], v[88:91], off offset:16
	global_store_dwordx4 v[106:107], v[240:243], off offset:-8
	s_nop 0
	v_or_b32_e32 v106, 0x100, v102
	v_mov_b32_e32 v107, v103
	v_lshl_add_u64 v[106:107], s[40:41], 0, v[106:107]
	v_mul_f32_e32 v89, v89, v89
	v_mul_f32_e32 v91, v91, v91
	v_fmac_f32_e32 v89, v88, v88
	v_fmac_f32_e32 v91, v90, v90
	v_add_f32_e32 v88, v89, v91
	v_add_f32_e32 v88, v92, v88
	v_or_b32_e32 v102, 0x108, v102
	v_lshl_add_u64 v[102:103], s[40:41], 0, v[102:103]
	s_nop 0
	v_pk_add_f32 v[86:87], v[86:87], v[210:211]
	v_pk_add_f32 v[84:85], v[84:85], v[208:209]
	v_cvt_pk_bf16_f32 v241, v86, v87
	v_cvt_pk_bf16_f32 v240, v84, v85
	global_store_dwordx4 v[104:105], v[84:87], off offset:512
	s_nop 0
	s_nop 0
	v_mul_f32_e32 v85, v85, v85
	v_mul_f32_e32 v87, v87, v87
	v_fmac_f32_e32 v85, v84, v84
	v_fmac_f32_e32 v87, v86, v86
	v_add_f32_e32 v84, v85, v87
	v_add_f32_e32 v86, v88, v84
	s_nop 0
	v_pk_add_f32 v[82:83], v[82:83], v[214:215]
	v_pk_add_f32 v[80:81], v[80:81], v[212:213]
	v_mov_b32_e32 v230, 0x140000
	v_lshl_add_u64 v[228:229], v[232:233], 0, v[230:231]
	global_load_dwordx4 v[200:203], v[228:229], off nt
	global_load_dwordx4 v[204:207], v[228:229], off offset:16 nt
	global_load_dwordx4 v[208:211], v[228:229], off offset:512 nt
	global_load_dwordx4 v[212:215], v[228:229], off offset:528 nt
	global_store_dwordx4 v[104:105], v[80:83], off offset:528
	v_cvt_pk_bf16_f32 v242, v80, v81
	v_cvt_pk_bf16_f32 v243, v82, v83
	v_mul_f32_e32 v81, v81, v81
	v_mul_f32_e32 v83, v83, v83
	v_fmac_f32_e32 v81, v80, v80
	v_fmac_f32_e32 v83, v82, v82
	v_add_f32_e32 v80, v81, v83
	v_add_f32_e32 v80, v86, v80
	v_mov_b32_e32 v81, v80
	s_nop 1
	v_permlane16_swap_b32 v80, v81
	global_store_dwordx4 v[102:103], v[240:243], off offset:-8
	v_add_f32_e32 v80, v80, v81
	v_mov_b32_e32 v81, v80
	s_nop 1
	v_permlane32_swap_b32 v80, v81
	s_and_saveexec_b64 s[12:13], s[2:3]
	s_cbranch_execz .LBB0_1611
	v_lshl_add_u64 v[82:83], v[96:97], 2, s[6:7]
	v_add_f32_e32 v80, v80, v81
	global_atomic_add_f32 v[82:83], v80, off
; __device__ __forceinline__ unsigned pk2(float lo, float hi) { f32x2_t v = {lo, hi}; bf16x2_t b = __builtin_convertvector(v, bf16x2_t); return __builtin_bit_cast(unsigned, b); }
; __device__ __forceinline__ float xor16_sum(float v) { float a = v, b = v; swap16(a, b); return a + b; }
; __device__ __forceinline__ float xor32_sum(float v) { float a = v, b = v; swap32(a, b); return a + b; }
;     __device__ __forceinline__ void operator()(const f32x4 (&acc)[2][2][4][2], const Unit& u, int wr, int wc, int fr, int fq) const {
;     ...
;         for (int ai = 0; ai < 2; ++ai)
; #pragma unroll
;             for (int m = 0; m < 4; ++m) {
;                 const int row = row0 + ai * HALF + m * 16; float sq = 0.f;
; #pragma unroll
;                 for (int bj = 0; bj < 2; ++bj)
; #pragma unroll
;                     for (int n = 0; n < 2; ++n) {
;                         const size_t idx = (size_t)row * ldc + u.pn * BM + bj * HALF + wc * 32 + 8 * fq + 4 * n;
;                         const f32x4 b = *(const f32x4*)(base + idx);
;                         const f32x4 v = b + acc[ai][bj][m][n] * alpha;
;                         *(f32x4*)(out + idx) = v;
;                         if (NORM) { u32x2 w; w.x = pk2(v[0], v[1]); w.y = pk2(v[2], v[3]); *(u32x2*)(xb + idx) = w; sq += (v[0] * v[0] + v[1] * v[1]) + (v[2] * v[2] + v[3] * v[3]); }
;                     }
;                 if (NORM) { sq = xor16_sum(sq); sq = xor32_sum(sq); if (fq == 0) __hip_atomic_fetch_add(ss + row, sq, __ATOMIC_RELAXED, __HIP_MEMORY_SCOPE_AGENT); }
.LBB0_1611:
	s_or_b64 exec, exec, s[12:13]
	v_or_b32_e32 v80, 48, v148
	v_ashrrev_i32_e32 v81, 31, v80
	v_lshlrev_b64 v[82:83], 11, v[80:81]
	v_lshl_add_u64 v[86:87], v[82:83], 0, v[146:147]
	v_lshl_add_u64 v[88:89], v[86:87], 2, s[30:31]
	s_nop 0
	v_lshlrev_b64 v[86:87], 1, v[86:87]
	v_lshl_add_u64 v[90:91], s[40:41], 0, v[86:87]
	s_nop 0
	s_waitcnt vmcnt(30)
	v_pk_add_f32 v[78:79], v[78:79], v[218:219]
	v_pk_add_f32 v[76:77], v[76:77], v[216:217]
	v_cvt_pk_bf16_f32 v241, v78, v79
	v_cvt_pk_bf16_f32 v240, v76, v77
	global_store_dwordx4 v[88:89], v[76:79], off
	s_nop 0
	s_nop 0
	v_or_b32_e32 v90, 8, v86
	v_mov_b32_e32 v91, v87
	v_lshl_add_u64 v[90:91], s[40:41], 0, v[90:91]
	v_mul_f32_e32 v77, v77, v77
	v_mul_f32_e32 v79, v79, v79
	v_fmac_f32_e32 v77, v76, v76
	v_fmac_f32_e32 v79, v78, v78
	v_add_f32_e32 v76, v77, v79
	s_nop 0
	v_pk_add_f32 v[74:75], v[74:75], v[222:223]
	v_pk_add_f32 v[72:73], v[72:73], v[220:221]
	v_cvt_pk_bf16_f32 v243, v74, v75
	v_cvt_pk_bf16_f32 v242, v72, v73
	global_store_dwordx4 v[88:89], v[72:75], off offset:16
	global_store_dwordx4 v[90:91], v[240:243], off offset:-8
	s_nop 0
	v_or_b32_e32 v90, 0x100, v86
	v_mov_b32_e32 v91, v87
	v_lshl_add_u64 v[90:91], s[40:41], 0, v[90:91]
	v_mul_f32_e32 v73, v73, v73
	v_mul_f32_e32 v75, v75, v75
	v_fmac_f32_e32 v73, v72, v72
	v_fmac_f32_e32 v75, v74, v74
	v_add_f32_e32 v72, v73, v75
	v_add_f32_e32 v72, v76, v72
	v_or_b32_e32 v86, 0x108, v86
	v_lshl_add_u64 v[86:87], s[40:41], 0, v[86:87]
	s_nop 0
	v_pk_add_f32 v[70:71], v[70:71], v[226:227]
	v_pk_add_f32 v[68:69], v[68:69], v[224:225]
	v_cvt_pk_bf16_f32 v241, v70, v71
	v_cvt_pk_bf16_f32 v240, v68, v69
	global_store_dwordx4 v[88:89], v[68:71], off offset:512
	s_nop 0
	s_nop 0
	v_mul_f32_e32 v69, v69, v69
	v_mul_f32_e32 v71, v71, v71
	v_fmac_f32_e32 v69, v68, v68
	v_fmac_f32_e32 v71, v70, v70
	v_add_f32_e32 v68, v69, v71
	v_add_f32_e32 v70, v72, v68
	s_nop 0
	v_pk_add_f32 v[66:67], v[66:67], v[236:237]
	v_pk_add_f32 v[64:65], v[64:65], v[234:235]
	v_mov_b32_e32 v230, 0x160000
	v_lshl_add_u64 v[228:229], v[232:233], 0, v[230:231]
	global_load_dwordx4 v[216:219], v[228:229], off nt
	global_load_dwordx4 v[220:223], v[228:229], off offset:16 nt
	global_load_dwordx4 v[224:227], v[228:229], off offset:512 nt
	global_load_dwordx4 v[234:237], v[228:229], off offset:528 nt
	global_store_dwordx4 v[88:89], v[64:67], off offset:528
	v_cvt_pk_bf16_f32 v242, v64, v65
	v_cvt_pk_bf16_f32 v243, v66, v67
	v_mul_f32_e32 v65, v65, v65
	v_mul_f32_e32 v67, v67, v67
	v_fmac_f32_e32 v65, v64, v64
	v_fmac_f32_e32 v67, v66, v66
	v_add_f32_e32 v64, v65, v67
	v_add_f32_e32 v64, v70, v64
	v_mov_b32_e32 v65, v64
	s_nop 1
	v_permlane16_swap_b32 v64, v65
	global_store_dwordx4 v[86:87], v[240:243], off offset:-8
	v_add_f32_e32 v64, v64, v65
	v_mov_b32_e32 v65, v64
	s_nop 1
	v_permlane32_swap_b32 v64, v65
	s_and_saveexec_b64 s[12:13], s[2:3]
	s_cbranch_execz .LBB0_1613
	v_lshl_add_u64 v[66:67], v[80:81], 2, s[6:7]
	v_add_f32_e32 v64, v64, v65
	global_atomic_add_f32 v[66:67], v64, off
.LBB0_1613:
	s_or_b64 exec, exec, s[12:13]
	v_add_u32_e32 v64, 0x80, v148
	v_ashrrev_i32_e32 v65, 31, v64
	v_lshlrev_b64 v[66:67], 11, v[64:65]
	v_lshl_add_u64 v[70:71], v[66:67], 0, v[146:147]
	v_lshl_add_u64 v[72:73], v[70:71], 2, s[30:31]
	s_nop 0
	v_lshlrev_b64 v[70:71], 1, v[70:71]
	v_lshl_add_u64 v[74:75], s[40:41], 0, v[70:71]
	s_nop 0
	s_waitcnt vmcnt(32)
	v_pk_add_f32 v[62:63], v[62:63], v[166:167]
	v_pk_add_f32 v[60:61], v[60:61], v[164:165]
	v_cvt_pk_bf16_f32 v241, v62, v63
	v_cvt_pk_bf16_f32 v240, v60, v61
	global_store_dwordx4 v[72:73], v[60:63], off
	s_nop 0
	s_nop 0
	v_or_b32_e32 v74, 8, v70
	v_mov_b32_e32 v75, v71
	v_lshl_add_u64 v[74:75], s[40:41], 0, v[74:75]
	v_mul_f32_e32 v61, v61, v61
	v_mul_f32_e32 v63, v63, v63
	v_fmac_f32_e32 v61, v60, v60
	v_fmac_f32_e32 v63, v62, v62
	v_add_f32_e32 v60, v61, v63
	s_nop 0
	v_pk_add_f32 v[58:59], v[58:59], v[170:171]
	v_pk_add_f32 v[56:57], v[56:57], v[168:169]
	v_cvt_pk_bf16_f32 v243, v58, v59
	v_cvt_pk_bf16_f32 v242, v56, v57
	global_store_dwordx4 v[72:73], v[56:59], off offset:16
	global_store_dwordx4 v[74:75], v[240:243], off offset:-8
	s_nop 0
	v_or_b32_e32 v74, 0x100, v70
	v_mov_b32_e32 v75, v71
	v_lshl_add_u64 v[74:75], s[40:41], 0, v[74:75]
	v_mul_f32_e32 v57, v57, v57
	v_mul_f32_e32 v59, v59, v59
	v_fmac_f32_e32 v57, v56, v56
	v_fmac_f32_e32 v59, v58, v58
	v_add_f32_e32 v56, v57, v59
	v_add_f32_e32 v56, v60, v56
	v_or_b32_e32 v70, 0x108, v70
	v_lshl_add_u64 v[70:71], s[40:41], 0, v[70:71]
	s_nop 0
	v_pk_add_f32 v[54:55], v[54:55], v[174:175]
	v_pk_add_f32 v[52:53], v[52:53], v[172:173]
	v_cvt_pk_bf16_f32 v241, v54, v55
	v_cvt_pk_bf16_f32 v240, v52, v53
	global_store_dwordx4 v[72:73], v[52:55], off offset:512
	s_nop 0
	s_nop 0
	v_mul_f32_e32 v53, v53, v53
	v_mul_f32_e32 v55, v55, v55
	v_fmac_f32_e32 v53, v52, v52
	v_fmac_f32_e32 v55, v54, v54
	v_add_f32_e32 v52, v53, v55
	v_add_f32_e32 v54, v56, v52
	s_nop 0
	v_pk_add_f32 v[50:51], v[50:51], v[178:179]
	v_pk_add_f32 v[48:49], v[48:49], v[176:177]
	global_store_dwordx4 v[72:73], v[48:51], off offset:528
	v_cvt_pk_bf16_f32 v242, v48, v49
	v_cvt_pk_bf16_f32 v243, v50, v51
	v_mul_f32_e32 v49, v49, v49
	v_mul_f32_e32 v51, v51, v51
	v_fmac_f32_e32 v49, v48, v48
	v_fmac_f32_e32 v51, v50, v50
	v_add_f32_e32 v48, v49, v51
	v_add_f32_e32 v48, v54, v48
	v_mov_b32_e32 v49, v48
	s_nop 1
	v_permlane16_swap_b32 v48, v49
	global_store_dwordx4 v[70:71], v[240:243], off offset:-8
	v_add_f32_e32 v48, v48, v49
	v_mov_b32_e32 v49, v48
	s_nop 1
	v_permlane32_swap_b32 v48, v49
	s_and_saveexec_b64 s[12:13], s[2:3]
	s_cbranch_execz .LBB0_1615
	v_lshl_add_u64 v[50:51], v[64:65], 2, s[6:7]
	v_add_f32_e32 v48, v48, v49
	global_atomic_add_f32 v[50:51], v48, off
; __device__ __forceinline__ unsigned pk2(float lo, float hi) { f32x2_t v = {lo, hi}; bf16x2_t b = __builtin_convertvector(v, bf16x2_t); return __builtin_bit_cast(unsigned, b); }
; __device__ __forceinline__ float xor16_sum(float v) { float a = v, b = v; swap16(a, b); return a + b; }
; __device__ __forceinline__ float xor32_sum(float v) { float a = v, b = v; swap32(a, b); return a + b; }
;     __device__ __forceinline__ void operator()(const f32x4 (&acc)[2][2][4][2], const Unit& u, int wr, int wc, int fr, int fq) const {
;     ...
;         for (int ai = 0; ai < 2; ++ai)
; #pragma unroll
;             for (int m = 0; m < 4; ++m) {
;                 const int row = row0 + ai * HALF + m * 16; float sq = 0.f;
; #pragma unroll
;                 for (int bj = 0; bj < 2; ++bj)
; #pragma unroll
;                     for (int n = 0; n < 2; ++n) {
;                         const size_t idx = (size_t)row * ldc + u.pn * BM + bj * HALF + wc * 32 + 8 * fq + 4 * n;
;                         const f32x4 b = *(const f32x4*)(base + idx);
;                         const f32x4 v = b + acc[ai][bj][m][n] * alpha;
;                         *(f32x4*)(out + idx) = v;
;                         if (NORM) { u32x2 w; w.x = pk2(v[0], v[1]); w.y = pk2(v[2], v[3]); *(u32x2*)(xb + idx) = w; sq += (v[0] * v[0] + v[1] * v[1]) + (v[2] * v[2] + v[3] * v[3]); }
;                     }
;                 if (NORM) { sq = xor16_sum(sq); sq = xor32_sum(sq); if (fq == 0) __hip_atomic_fetch_add(ss + row, sq, __ATOMIC_RELAXED, __HIP_MEMORY_SCOPE_AGENT); }
.LBB0_1615:
	s_or_b64 exec, exec, s[12:13]
	v_add_u32_e32 v48, 0x90, v148
	v_ashrrev_i32_e32 v49, 31, v48
	v_lshlrev_b64 v[50:51], 11, v[48:49]
	v_lshl_add_u64 v[54:55], v[50:51], 0, v[146:147]
	v_lshl_add_u64 v[56:57], v[54:55], 2, s[30:31]
	s_nop 0
	v_lshlrev_b64 v[54:55], 1, v[54:55]
	v_lshl_add_u64 v[58:59], s[40:41], 0, v[54:55]
	s_nop 0
	s_waitcnt vmcnt(28)
	v_pk_add_f32 v[46:47], v[46:47], v[182:183]
	v_pk_add_f32 v[44:45], v[44:45], v[180:181]
	v_cvt_pk_bf16_f32 v241, v46, v47
	v_cvt_pk_bf16_f32 v240, v44, v45
	global_store_dwordx4 v[56:57], v[44:47], off
	s_nop 0
	s_nop 0
	v_or_b32_e32 v58, 8, v54
	v_mov_b32_e32 v59, v55
	v_lshl_add_u64 v[58:59], s[40:41], 0, v[58:59]
	v_mul_f32_e32 v45, v45, v45
	v_mul_f32_e32 v47, v47, v47
	v_fmac_f32_e32 v45, v44, v44
	v_fmac_f32_e32 v47, v46, v46
	v_add_f32_e32 v44, v45, v47
	s_nop 0
	v_pk_add_f32 v[42:43], v[42:43], v[190:191]
	v_pk_add_f32 v[40:41], v[40:41], v[188:189]
	v_cvt_pk_bf16_f32 v243, v42, v43
	v_cvt_pk_bf16_f32 v242, v40, v41
	global_store_dwordx4 v[56:57], v[40:43], off offset:16
	global_store_dwordx4 v[58:59], v[240:243], off offset:-8
	s_nop 0
	v_or_b32_e32 v58, 0x100, v54
	v_mov_b32_e32 v59, v55
	v_lshl_add_u64 v[58:59], s[40:41], 0, v[58:59]
	v_mul_f32_e32 v41, v41, v41
	v_mul_f32_e32 v43, v43, v43
	v_fmac_f32_e32 v41, v40, v40
	v_fmac_f32_e32 v43, v42, v42
	v_add_f32_e32 v40, v41, v43
	v_add_f32_e32 v40, v44, v40
	v_or_b32_e32 v54, 0x108, v54
	v_lshl_add_u64 v[54:55], s[40:41], 0, v[54:55]
	s_nop 0
	v_pk_add_f32 v[38:39], v[38:39], v[194:195]
	v_pk_add_f32 v[36:37], v[36:37], v[192:193]
	v_cvt_pk_bf16_f32 v241, v38, v39
	v_cvt_pk_bf16_f32 v240, v36, v37
	global_store_dwordx4 v[56:57], v[36:39], off offset:512
	s_nop 0
	s_nop 0
	v_mul_f32_e32 v37, v37, v37
	v_mul_f32_e32 v39, v39, v39
	v_fmac_f32_e32 v37, v36, v36
	v_fmac_f32_e32 v39, v38, v38
	v_add_f32_e32 v36, v37, v39
	v_add_f32_e32 v38, v40, v36
	s_nop 0
	v_pk_add_f32 v[34:35], v[34:35], v[198:199]
	v_pk_add_f32 v[32:33], v[32:33], v[196:197]
	global_store_dwordx4 v[56:57], v[32:35], off offset:528
	v_cvt_pk_bf16_f32 v242, v32, v33
	v_cvt_pk_bf16_f32 v243, v34, v35
	v_mul_f32_e32 v33, v33, v33
	v_mul_f32_e32 v35, v35, v35
	v_fmac_f32_e32 v33, v32, v32
	v_fmac_f32_e32 v35, v34, v34
	v_add_f32_e32 v32, v33, v35
	v_add_f32_e32 v32, v38, v32
	v_mov_b32_e32 v33, v32
	s_nop 1
	v_permlane16_swap_b32 v32, v33
	global_store_dwordx4 v[54:55], v[240:243], off offset:-8
	v_add_f32_e32 v32, v32, v33
	v_mov_b32_e32 v33, v32
	s_nop 1
	v_permlane32_swap_b32 v32, v33
	s_and_saveexec_b64 s[12:13], s[2:3]
	s_cbranch_execz .LBB0_1617
	v_lshl_add_u64 v[34:35], v[48:49], 2, s[6:7]
	v_add_f32_e32 v32, v32, v33
	global_atomic_add_f32 v[34:35], v32, off
; __device__ __forceinline__ unsigned pk2(float lo, float hi) { f32x2_t v = {lo, hi}; bf16x2_t b = __builtin_convertvector(v, bf16x2_t); return __builtin_bit_cast(unsigned, b); }
; __device__ __forceinline__ float xor16_sum(float v) { float a = v, b = v; swap16(a, b); return a + b; }
; __device__ __forceinline__ float xor32_sum(float v) { float a = v, b = v; swap32(a, b); return a + b; }
;     __device__ __forceinline__ void operator()(const f32x4 (&acc)[2][2][4][2], const Unit& u, int wr, int wc, int fr, int fq) const {
;     ...
;         for (int ai = 0; ai < 2; ++ai)
; #pragma unroll
;             for (int m = 0; m < 4; ++m) {
;                 const int row = row0 + ai * HALF + m * 16; float sq = 0.f;
; #pragma unroll
;                 for (int bj = 0; bj < 2; ++bj)
; #pragma unroll
;                     for (int n = 0; n < 2; ++n) {
;                         const size_t idx = (size_t)row * ldc + u.pn * BM + bj * HALF + wc * 32 + 8 * fq + 4 * n;
;                         const f32x4 b = *(const f32x4*)(base + idx);
;                         const f32x4 v = b + acc[ai][bj][m][n] * alpha;
;                         *(f32x4*)(out + idx) = v;
;                         if (NORM) { u32x2 w; w.x = pk2(v[0], v[1]); w.y = pk2(v[2], v[3]); *(u32x2*)(xb + idx) = w; sq += (v[0] * v[0] + v[1] * v[1]) + (v[2] * v[2] + v[3] * v[3]); }
;                     }
;                 if (NORM) { sq = xor16_sum(sq); sq = xor32_sum(sq); if (fq == 0) __hip_atomic_fetch_add(ss + row, sq, __ATOMIC_RELAXED, __HIP_MEMORY_SCOPE_AGENT); }
.LBB0_1617:
	s_or_b64 exec, exec, s[12:13]
	v_add_u32_e32 v32, 0xa0, v148
	v_ashrrev_i32_e32 v33, 31, v32
	v_lshlrev_b64 v[34:35], 11, v[32:33]
	v_lshl_add_u64 v[38:39], v[34:35], 0, v[146:147]
	v_lshl_add_u64 v[40:41], v[38:39], 2, s[30:31]
	s_nop 0
	v_lshlrev_b64 v[38:39], 1, v[38:39]
	v_lshl_add_u64 v[42:43], s[40:41], 0, v[38:39]
	s_nop 0
	s_waitcnt vmcnt(24)
	v_pk_add_f32 v[30:31], v[30:31], v[202:203]
	v_pk_add_f32 v[28:29], v[28:29], v[200:201]
	v_cvt_pk_bf16_f32 v241, v30, v31
	v_cvt_pk_bf16_f32 v240, v28, v29
	global_store_dwordx4 v[40:41], v[28:31], off
	s_nop 0
	s_nop 0
	v_or_b32_e32 v42, 8, v38
	v_mov_b32_e32 v43, v39
	v_lshl_add_u64 v[42:43], s[40:41], 0, v[42:43]
	v_mul_f32_e32 v29, v29, v29
	v_mul_f32_e32 v31, v31, v31
	v_fmac_f32_e32 v29, v28, v28
	v_fmac_f32_e32 v31, v30, v30
	v_add_f32_e32 v28, v29, v31
	s_nop 0
	v_pk_add_f32 v[26:27], v[26:27], v[206:207]
	v_pk_add_f32 v[24:25], v[24:25], v[204:205]
	v_cvt_pk_bf16_f32 v243, v26, v27
	v_cvt_pk_bf16_f32 v242, v24, v25
	global_store_dwordx4 v[40:41], v[24:27], off offset:16
	global_store_dwordx4 v[42:43], v[240:243], off offset:-8
	s_nop 0
	v_or_b32_e32 v42, 0x100, v38
	v_mov_b32_e32 v43, v39
	v_lshl_add_u64 v[42:43], s[40:41], 0, v[42:43]
	v_mul_f32_e32 v25, v25, v25
	v_mul_f32_e32 v27, v27, v27
	v_fmac_f32_e32 v25, v24, v24
	v_fmac_f32_e32 v27, v26, v26
	v_add_f32_e32 v24, v25, v27
	v_add_f32_e32 v24, v28, v24
	v_or_b32_e32 v38, 0x108, v38
	v_lshl_add_u64 v[38:39], s[40:41], 0, v[38:39]
	s_nop 0
	v_pk_add_f32 v[22:23], v[22:23], v[210:211]
	v_pk_add_f32 v[20:21], v[20:21], v[208:209]
	v_cvt_pk_bf16_f32 v241, v22, v23
	v_cvt_pk_bf16_f32 v240, v20, v21
	global_store_dwordx4 v[40:41], v[20:23], off offset:512
	s_nop 0
	s_nop 0
	v_mul_f32_e32 v21, v21, v21
	v_mul_f32_e32 v23, v23, v23
	v_fmac_f32_e32 v21, v20, v20
	v_fmac_f32_e32 v23, v22, v22
	v_add_f32_e32 v20, v21, v23
	v_add_f32_e32 v22, v24, v20
	s_nop 0
	v_pk_add_f32 v[18:19], v[18:19], v[214:215]
	v_pk_add_f32 v[16:17], v[16:17], v[212:213]
	global_store_dwordx4 v[40:41], v[16:19], off offset:528
	v_cvt_pk_bf16_f32 v242, v16, v17
	v_cvt_pk_bf16_f32 v243, v18, v19
	v_mul_f32_e32 v17, v17, v17
	v_mul_f32_e32 v19, v19, v19
	v_fmac_f32_e32 v17, v16, v16
	v_fmac_f32_e32 v19, v18, v18
	v_add_f32_e32 v16, v17, v19
	v_add_f32_e32 v16, v22, v16
	v_mov_b32_e32 v17, v16
	s_nop 1
	v_permlane16_swap_b32 v16, v17
	global_store_dwordx4 v[38:39], v[240:243], off offset:-8
	v_add_f32_e32 v16, v16, v17
	v_mov_b32_e32 v17, v16
	s_nop 1
	v_permlane32_swap_b32 v16, v17
	s_and_saveexec_b64 s[12:13], s[2:3]
	s_cbranch_execz .LBB0_1619
	v_lshl_add_u64 v[18:19], v[32:33], 2, s[6:7]
	v_add_f32_e32 v16, v16, v17
	global_atomic_add_f32 v[18:19], v16, off
.LBB0_1619:
	s_or_b64 exec, exec, s[12:13]
	v_add_u32_e32 v16, 0xb0, v148
	v_ashrrev_i32_e32 v17, 31, v16
	v_lshlrev_b64 v[18:19], 11, v[16:17]
	v_lshl_add_u64 v[22:23], v[18:19], 0, v[146:147]
	v_lshl_add_u64 v[24:25], v[22:23], 2, s[30:31]
	s_nop 0
	v_lshlrev_b64 v[22:23], 1, v[22:23]
	v_lshl_add_u64 v[26:27], s[40:41], 0, v[22:23]
	s_nop 0
	s_waitcnt vmcnt(20)
	v_pk_add_f32 v[14:15], v[14:15], v[218:219]
	v_pk_add_f32 v[12:13], v[12:13], v[216:217]
	v_cvt_pk_bf16_f32 v241, v14, v15
	v_cvt_pk_bf16_f32 v240, v12, v13
	global_store_dwordx4 v[24:25], v[12:15], off
	s_nop 0
	s_nop 0
	v_or_b32_e32 v26, 8, v22
	v_mov_b32_e32 v27, v23
	v_lshl_add_u64 v[26:27], s[40:41], 0, v[26:27]
	v_mul_f32_e32 v13, v13, v13
	v_mul_f32_e32 v15, v15, v15
	v_fmac_f32_e32 v13, v12, v12
	v_fmac_f32_e32 v15, v14, v14
	v_add_f32_e32 v12, v13, v15
	s_nop 0
	v_pk_add_f32 v[10:11], v[10:11], v[222:223]
	v_pk_add_f32 v[8:9], v[8:9], v[220:221]
	v_cvt_pk_bf16_f32 v243, v10, v11
	v_cvt_pk_bf16_f32 v242, v8, v9
	global_store_dwordx4 v[24:25], v[8:11], off offset:16
	global_store_dwordx4 v[26:27], v[240:243], off offset:-8
	s_nop 0
	v_or_b32_e32 v26, 0x100, v22
	v_mov_b32_e32 v27, v23
	v_lshl_add_u64 v[26:27], s[40:41], 0, v[26:27]
	v_mul_f32_e32 v9, v9, v9
	v_mul_f32_e32 v11, v11, v11
	v_fmac_f32_e32 v9, v8, v8
	v_fmac_f32_e32 v11, v10, v10
	v_add_f32_e32 v8, v9, v11
	v_add_f32_e32 v8, v12, v8
	v_or_b32_e32 v22, 0x108, v22
	v_lshl_add_u64 v[22:23], s[40:41], 0, v[22:23]
	s_nop 0
	v_pk_add_f32 v[6:7], v[6:7], v[226:227]
	v_pk_add_f32 v[4:5], v[4:5], v[224:225]
	v_cvt_pk_bf16_f32 v241, v6, v7
	v_cvt_pk_bf16_f32 v240, v4, v5
	global_store_dwordx4 v[24:25], v[4:7], off offset:512
	s_nop 0
	s_nop 0
	v_mul_f32_e32 v5, v5, v5
	v_mul_f32_e32 v7, v7, v7
	v_fmac_f32_e32 v5, v4, v4
	v_fmac_f32_e32 v7, v6, v6
	v_add_f32_e32 v4, v5, v7
	v_add_f32_e32 v6, v8, v4
	s_nop 0
	v_pk_add_f32 v[2:3], v[2:3], v[236:237]
	v_pk_add_f32 v[0:1], v[0:1], v[234:235]
	global_store_dwordx4 v[24:25], v[0:3], off offset:528
	v_cvt_pk_bf16_f32 v242, v0, v1
	v_cvt_pk_bf16_f32 v243, v2, v3
	v_mul_f32_e32 v1, v1, v1
	v_mul_f32_e32 v3, v3, v3
	v_fmac_f32_e32 v1, v0, v0
	v_fmac_f32_e32 v3, v2, v2
	v_add_f32_e32 v0, v1, v3
	v_add_f32_e32 v0, v6, v0
	v_mov_b32_e32 v1, v0
	s_nop 1
	v_permlane16_swap_b32 v0, v1
	global_store_dwordx4 v[22:23], v[240:243], off offset:-8
	v_add_f32_e32 v0, v0, v1
	v_mov_b32_e32 v1, v0
	s_nop 1
	v_permlane32_swap_b32 v0, v1
	s_and_saveexec_b64 s[12:13], s[2:3]
	s_cbranch_execz .LBB0_1621
	v_lshl_add_u64 v[2:3], v[16:17], 2, s[6:7]
	v_add_f32_e32 v0, v0, v1
	global_atomic_add_f32 v[2:3], v0, off

; __global__ void __launch_bounds__(512, 2) mega_fwd(Args args) {
	.amdhsa_kernel _Z8mega_fwd4Args
		.amdhsa_group_segment_fixed_size 0
		.amdhsa_private_segment_fixed_size 0
		.amdhsa_kernarg_size 536
		.amdhsa_user_sgpr_count 2
		.amdhsa_user_sgpr_dispatch_ptr 0
		.amdhsa_user_sgpr_queue_ptr 0
		.amdhsa_user_sgpr_kernarg_segment_ptr 1
		.amdhsa_user_sgpr_dispatch_id 0
		.amdhsa_user_sgpr_kernarg_preload_length 0
		.amdhsa_user_sgpr_kernarg_preload_offset 0
		.amdhsa_user_sgpr_private_segment_size 0
		.amdhsa_uses_dynamic_stack 0
		.amdhsa_enable_private_segment 0
		.amdhsa_system_sgpr_workgroup_id_x 1
		.amdhsa_system_sgpr_workgroup_id_y 0
		.amdhsa_system_sgpr_workgroup_id_z 0
		.amdhsa_system_sgpr_workgroup_info 0
		.amdhsa_system_vgpr_workitem_id 2
		.amdhsa_next_free_vgpr 248
		.amdhsa_next_free_sgpr 98
		.amdhsa_accum_offset 248
		.amdhsa_reserve_vcc 1
		.amdhsa_float_round_mode_32 0
		.amdhsa_float_round_mode_16_64 0
		.amdhsa_float_denorm_mode_32 3
		.amdhsa_float_denorm_mode_16_64 3
		.amdhsa_dx10_clamp 1
		.amdhsa_ieee_mode 1
		.amdhsa_fp16_overflow 0
		.amdhsa_tg_split 0
		.amdhsa_exception_fp_ieee_invalid_op 0
		.amdhsa_exception_fp_denorm_src 0
		.amdhsa_exception_fp_ieee_div_zero 0
		.amdhsa_exception_fp_ieee_overflow 0
		.amdhsa_exception_fp_ieee_underflow 0
		.amdhsa_exception_fp_ieee_inexact 0
		.amdhsa_exception_int_div_zero 0
	.end_amdhsa_kernel

; __global__ void __launch_bounds__(512, 2) mega_fwd(Args args) {
.Lfunc_end0:
	.size	_Z8mega_fwd4Args, .Lfunc_end0-_Z8mega_fwd4Args
	.set _Z8mega_fwd4Args.num_vgpr, 248
	.set _Z8mega_fwd4Args.num_agpr, 0
	.set _Z8mega_fwd4Args.numbered_sgpr, 98
	.set _Z8mega_fwd4Args.num_named_barrier, 0
	.set _Z8mega_fwd4Args.private_seg_size, 0
	.set _Z8mega_fwd4Args.uses_vcc, 1
	.set _Z8mega_fwd4Args.uses_flat_scratch, 0
	.set _Z8mega_fwd4Args.has_dyn_sized_stack, 0
	.set _Z8mega_fwd4Args.has_recursion, 0
	.set _Z8mega_fwd4Args.has_indirect_call, 0

; __global__ void __launch_bounds__(512, 2) mega_fwd(Args args) {
amdhsa.kernels:
  - .agpr_count:     0
    .args:
      - .offset:         0
        .size:           280
        .value_kind:     by_value
      - .offset:         280
        .size:           4
        .value_kind:     hidden_block_count_x
      - .offset:         284
        .size:           4
        .value_kind:     hidden_block_count_y
      - .offset:         288
        .size:           4
        .value_kind:     hidden_block_count_z
      - .offset:         292
        .size:           2
        .value_kind:     hidden_group_size_x
      - .offset:         294
        .size:           2
        .value_kind:     hidden_group_size_y
      - .offset:         296
        .size:           2
        .value_kind:     hidden_group_size_z
      - .offset:         298
        .size:           2
        .value_kind:     hidden_remainder_x
      - .offset:         300
        .size:           2
        .value_kind:     hidden_remainder_y
      - .offset:         302
        .size:           2
        .value_kind:     hidden_remainder_z
      - .offset:         320
        .size:           8
        .value_kind:     hidden_global_offset_x
      - .offset:         328
        .size:           8
        .value_kind:     hidden_global_offset_y
      - .offset:         336
        .size:           8
        .value_kind:     hidden_global_offset_z
      - .offset:         344
        .size:           2
        .value_kind:     hidden_grid_dims
      - .offset:         368
        .size:           8
        .value_kind:     hidden_multigrid_sync_arg
      - .offset:         400
        .size:           4
        .value_kind:     hidden_dynamic_lds_size
    .group_segment_fixed_size: 0
    .kernarg_segment_align: 8
    .kernarg_segment_size: 536
    .language:       OpenCL C
    .language_version:
      - 2
      - 0
    .max_flat_workgroup_size: 512
    .name:           _Z8mega_fwd4Args
    .private_segment_fixed_size: 0
    .sgpr_count:     104
    .sgpr_spill_count: 73
    .symbol:         _Z8mega_fwd4Args.kd
    .uniform_work_group_size: 1
    .uses_dynamic_stack: false
    .vgpr_count:     248
    .vgpr_spill_count: 0
    .wavefront_size: 64
